# mlp-up relu^2 epilogues: in-place canonicalising v_max before max(0,x) removed (wait states after x4 stores kept)
# baseline (speedup 1.0000x reference)
.LBB0_683:
	ds_read_b128 v[154:157], v151
	ds_read_b128 v[158:161], v151 offset:1024
	ds_read_b128 v[162:165], v151 offset:2048
	ds_read_b128 v[166:169], v151 offset:3072
	s_add_u32 s34, s30, 0xfffc0080
	s_addc_u32 s35, s31, -1
	s_cmp_eq_u32 s85, 12
	s_cselect_b32 s55, s19, s35
	s_cselect_b32 s54, s81, s34
	s_cselect_b32 s35, s17, s84
	s_cselect_b32 s34, s82, s83
	v_lshl_add_u64 v[202:203], s[30:31], 0, v[138:139]
	s_add_i32 m0, s29, 0xc000
	ds_read_b128 v[170:173], v152
	ds_read_b128 v[174:177], v152 offset:1024
	ds_read_b128 v[178:181], v152 offset:2048
	ds_read_b128 v[182:185], v152 offset:3072
	ds_read_b128 v[186:189], v152 offset:4096
	ds_read_b128 v[190:193], v152 offset:5120
	ds_read_b128 v[194:197], v152 offset:6144
	ds_read_b128 v[198:201], v152 offset:7168
	global_load_lds_dwordx4 v[202:203], off
	v_lshl_add_u64 v[202:203], s[30:31], 0, v[140:141]
	s_add_i32 m0, s29, 0xe000
	s_nop 0
	global_load_lds_dwordx4 v[202:203], off
	s_waitcnt lgkmcnt(8)
	s_barrier
	s_waitcnt lgkmcnt(0)
	s_waitcnt lgkmcnt(0)
	v_mfma_f32_16x16x32_bf16 v[124:127], v[154:157], v[170:173], v[124:127]
	v_mfma_f32_16x16x32_bf16 v[120:123], v[162:165], v[170:173], v[120:123]
	v_mfma_f32_16x16x32_bf16 v[108:111], v[154:157], v[178:181], v[108:111]
	v_mfma_f32_16x16x32_bf16 v[104:107], v[162:165], v[178:181], v[104:107]
	v_mfma_f32_16x16x32_bf16 v[92:95], v[154:157], v[186:189], v[92:95]
	v_mfma_f32_16x16x32_bf16 v[88:91], v[162:165], v[186:189], v[88:91]
	v_mfma_f32_16x16x32_bf16 v[76:79], v[154:157], v[194:197], v[76:79]
	v_mfma_f32_16x16x32_bf16 v[72:75], v[162:165], v[194:197], v[72:75]
	v_mfma_f32_16x16x32_bf16 v[124:127], v[158:161], v[174:177], v[124:127]
	v_mfma_f32_16x16x32_bf16 v[120:123], v[166:169], v[174:177], v[120:123]
	v_mfma_f32_16x16x32_bf16 v[108:111], v[158:161], v[182:185], v[108:111]
	v_mfma_f32_16x16x32_bf16 v[104:107], v[166:169], v[182:185], v[104:107]
	v_mfma_f32_16x16x32_bf16 v[92:95], v[158:161], v[190:193], v[92:95]
	v_mfma_f32_16x16x32_bf16 v[88:91], v[166:169], v[190:193], v[88:91]
	v_mfma_f32_16x16x32_bf16 v[76:79], v[158:161], v[198:201], v[76:79]
	v_mfma_f32_16x16x32_bf16 v[72:75], v[166:169], v[198:201], v[72:75]
	s_barrier
	s_add_i32 s86, s74, s60
	v_lshl_add_u64 v[218:219], s[34:35], 0, v[132:133]
	s_mov_b32 m0, s86
	ds_read_b128 v[202:205], v153
	ds_read_b128 v[206:209], v153 offset:1024
	ds_read_b128 v[210:213], v153 offset:2048
	ds_read_b128 v[214:217], v153 offset:3072
	global_load_lds_dwordx4 v[218:219], off
	v_lshl_add_u64 v[220:221], s[34:35], 0, v[136:137]
	s_add_i32 m0, s86, 0x2000
	s_nop 0
	global_load_lds_dwordx4 v[220:221], off
	s_barrier
	s_waitcnt lgkmcnt(0)
	s_waitcnt lgkmcnt(0)
	v_mfma_f32_16x16x32_bf16 v[116:119], v[202:205], v[170:173], v[116:119]
	v_mfma_f32_16x16x32_bf16 v[112:115], v[210:213], v[170:173], v[112:115]
	v_mfma_f32_16x16x32_bf16 v[100:103], v[202:205], v[178:181], v[100:103]
	v_mfma_f32_16x16x32_bf16 v[96:99], v[210:213], v[178:181], v[96:99]
	v_mfma_f32_16x16x32_bf16 v[84:87], v[202:205], v[186:189], v[84:87]
	v_mfma_f32_16x16x32_bf16 v[80:83], v[210:213], v[186:189], v[80:83]
	v_mfma_f32_16x16x32_bf16 v[68:71], v[202:205], v[194:197], v[68:71]
	v_mfma_f32_16x16x32_bf16 v[64:67], v[210:213], v[194:197], v[64:67]
	v_mfma_f32_16x16x32_bf16 v[116:119], v[206:209], v[174:177], v[116:119]
	v_mfma_f32_16x16x32_bf16 v[112:115], v[214:217], v[174:177], v[112:115]
	v_mfma_f32_16x16x32_bf16 v[100:103], v[206:209], v[182:185], v[100:103]
	v_mfma_f32_16x16x32_bf16 v[96:99], v[214:217], v[182:185], v[96:99]
	v_mfma_f32_16x16x32_bf16 v[84:87], v[206:209], v[190:193], v[84:87]
	v_mfma_f32_16x16x32_bf16 v[80:83], v[214:217], v[190:193], v[80:83]
	v_mfma_f32_16x16x32_bf16 v[68:71], v[206:209], v[198:201], v[68:71]
	v_mfma_f32_16x16x32_bf16 v[64:67], v[214:217], v[198:201], v[64:67]
	s_mov_b32 m0, s29
	v_lshl_add_u64 v[222:223], s[54:55], 0, v[130:131]
	s_barrier
	ds_read_b128 v[170:173], v152 offset:16384
	ds_read_b128 v[174:177], v152 offset:17408
	ds_read_b128 v[178:181], v152 offset:18432
	ds_read_b128 v[182:185], v152 offset:19456
	ds_read_b128 v[186:189], v152 offset:20480
	ds_read_b128 v[190:193], v152 offset:21504
	ds_read_b128 v[194:197], v152 offset:22528
	ds_read_b128 v[198:201], v152 offset:23552
	global_load_lds_dwordx4 v[222:223], off
	v_lshl_add_u64 v[224:225], s[54:55], 0, v[134:135]
	s_mov_b32 m0, s61
	s_nop 0
	global_load_lds_dwordx4 v[224:225], off
	s_barrier
	s_waitcnt lgkmcnt(0)
	s_waitcnt lgkmcnt(0)
	v_mfma_f32_16x16x32_bf16 v[60:63], v[154:157], v[170:173], v[60:63]
	v_mfma_f32_16x16x32_bf16 v[56:59], v[162:165], v[170:173], v[56:59]
	v_mfma_f32_16x16x32_bf16 v[44:47], v[154:157], v[178:181], v[44:47]
	v_mfma_f32_16x16x32_bf16 v[40:43], v[162:165], v[178:181], v[40:43]
	v_mfma_f32_16x16x32_bf16 v[28:31], v[154:157], v[186:189], v[28:31]
	v_mfma_f32_16x16x32_bf16 v[24:27], v[162:165], v[186:189], v[24:27]
	v_mfma_f32_16x16x32_bf16 v[12:15], v[154:157], v[194:197], v[12:15]
	v_mfma_f32_16x16x32_bf16 v[8:11], v[162:165], v[194:197], v[8:11]
	v_mfma_f32_16x16x32_bf16 v[60:63], v[158:161], v[174:177], v[60:63]
	v_mfma_f32_16x16x32_bf16 v[56:59], v[166:169], v[174:177], v[56:59]
	v_mfma_f32_16x16x32_bf16 v[44:47], v[158:161], v[182:185], v[44:47]
	v_mfma_f32_16x16x32_bf16 v[40:43], v[166:169], v[182:185], v[40:43]
	v_mfma_f32_16x16x32_bf16 v[28:31], v[158:161], v[190:193], v[28:31]
	v_mfma_f32_16x16x32_bf16 v[24:27], v[166:169], v[190:193], v[24:27]
	v_mfma_f32_16x16x32_bf16 v[12:15], v[158:161], v[198:201], v[12:15]
	v_mfma_f32_16x16x32_bf16 v[8:11], v[166:169], v[198:201], v[8:11]
	s_barrier
	s_add_u32 s86, s34, 0x40000
	s_addc_u32 s87, s35, 0
	s_add_i32 s88, s75, s60
	v_lshl_add_u64 v[154:155], s[86:87], 0, v[132:133]
	s_mov_b32 m0, s88
	s_nop 0
	global_load_lds_dwordx4 v[154:155], off
	v_lshl_add_u64 v[154:155], s[86:87], 0, v[136:137]
	s_add_i32 m0, s88, 0x2000
	s_nop 0
	global_load_lds_dwordx4 v[154:155], off
	s_waitcnt vmcnt(6)
	s_barrier
	v_mfma_f32_16x16x32_bf16 v[52:55], v[202:205], v[170:173], v[52:55]
	v_mfma_f32_16x16x32_bf16 v[48:51], v[210:213], v[170:173], v[48:51]
	v_mfma_f32_16x16x32_bf16 v[36:39], v[202:205], v[178:181], v[36:39]
	v_mfma_f32_16x16x32_bf16 v[32:35], v[210:213], v[178:181], v[32:35]
	v_mfma_f32_16x16x32_bf16 v[20:23], v[202:205], v[186:189], v[20:23]
	v_mfma_f32_16x16x32_bf16 v[16:19], v[210:213], v[186:189], v[16:19]
	v_mfma_f32_16x16x32_bf16 v[4:7], v[202:205], v[194:197], v[4:7]
	v_mfma_f32_16x16x32_bf16 v[0:3], v[210:213], v[194:197], v[0:3]
	v_mfma_f32_16x16x32_bf16 v[52:55], v[206:209], v[174:177], v[52:55]
	v_mfma_f32_16x16x32_bf16 v[48:51], v[214:217], v[174:177], v[48:51]
	v_mfma_f32_16x16x32_bf16 v[36:39], v[206:209], v[182:185], v[36:39]
	v_mfma_f32_16x16x32_bf16 v[32:35], v[214:217], v[182:185], v[32:35]
	v_mfma_f32_16x16x32_bf16 v[20:23], v[206:209], v[190:193], v[20:23]
	v_mfma_f32_16x16x32_bf16 v[16:19], v[214:217], v[190:193], v[16:19]
	v_mfma_f32_16x16x32_bf16 v[4:7], v[206:209], v[198:201], v[4:7]
	v_mfma_f32_16x16x32_bf16 v[0:3], v[214:217], v[198:201], v[0:3]
	s_add_i32 s86, 0, 0x18000
	v_add_u32_e32 v166, s86, v149
	s_barrier
	ds_read_b128 v[154:157], v166
	ds_read_b128 v[158:161], v166 offset:1024
	ds_read_b128 v[162:165], v166 offset:2048
	ds_read_b128 v[166:169], v166 offset:3072
	s_add_u32 s54, s54, 0x40000
	s_addc_u32 s55, s55, 0
	s_mov_b32 m0, s62
	v_lshl_add_u64 v[202:203], s[54:55], 0, v[130:131]
	ds_read_b128 v[170:173], v152 offset:32768
	ds_read_b128 v[174:177], v152 offset:33792
	ds_read_b128 v[178:181], v152 offset:34816
	ds_read_b128 v[182:185], v152 offset:35840
	ds_read_b128 v[186:189], v152 offset:36864
	ds_read_b128 v[190:193], v152 offset:37888
	ds_read_b128 v[194:197], v152 offset:38912
	ds_read_b128 v[198:201], v152 offset:39936
	global_load_lds_dwordx4 v[202:203], off
	v_lshl_add_u64 v[202:203], s[54:55], 0, v[134:135]
	s_mov_b32 m0, s63
	s_nop 0
	global_load_lds_dwordx4 v[202:203], off
	s_waitcnt lgkmcnt(8)
	s_barrier
	s_waitcnt lgkmcnt(0)
	s_waitcnt lgkmcnt(0)
	v_mfma_f32_16x16x32_bf16 v[124:127], v[154:157], v[170:173], v[124:127]
	v_mfma_f32_16x16x32_bf16 v[120:123], v[162:165], v[170:173], v[120:123]
	v_mfma_f32_16x16x32_bf16 v[108:111], v[154:157], v[178:181], v[108:111]
	v_mfma_f32_16x16x32_bf16 v[104:107], v[162:165], v[178:181], v[104:107]
	v_mfma_f32_16x16x32_bf16 v[92:95], v[154:157], v[186:189], v[92:95]
	v_mfma_f32_16x16x32_bf16 v[88:91], v[162:165], v[186:189], v[88:91]
	v_mfma_f32_16x16x32_bf16 v[76:79], v[154:157], v[194:197], v[76:79]
	v_mfma_f32_16x16x32_bf16 v[72:75], v[162:165], v[194:197], v[72:75]
	v_mfma_f32_16x16x32_bf16 v[124:127], v[158:161], v[174:177], v[124:127]
	v_mfma_f32_16x16x32_bf16 v[120:123], v[166:169], v[174:177], v[120:123]
	v_mfma_f32_16x16x32_bf16 v[108:111], v[158:161], v[182:185], v[108:111]
	v_mfma_f32_16x16x32_bf16 v[104:107], v[166:169], v[182:185], v[104:107]
	v_mfma_f32_16x16x32_bf16 v[92:95], v[158:161], v[190:193], v[92:95]
	v_mfma_f32_16x16x32_bf16 v[88:91], v[166:169], v[190:193], v[88:91]
	v_mfma_f32_16x16x32_bf16 v[76:79], v[158:161], v[198:201], v[76:79]
	v_mfma_f32_16x16x32_bf16 v[72:75], v[166:169], v[198:201], v[72:75]
	s_barrier
	s_add_i32 s54, 0, 0x1c000
	s_add_i32 s55, s86, s60
	v_add_u32_e32 v214, s54, v149
	v_lshl_add_u64 v[218:219], v[218:219], 0, s[8:9]
	s_mov_b32 m0, s55
	ds_read_b128 v[202:205], v214
	ds_read_b128 v[206:209], v214 offset:1024
	ds_read_b128 v[210:213], v214 offset:2048
	ds_read_b128 v[214:217], v214 offset:3072
	global_load_lds_dwordx4 v[218:219], off
	v_lshl_add_u64 v[218:219], v[220:221], 0, s[8:9]
	s_add_i32 m0, s55, 0x2000
	s_nop 0
	global_load_lds_dwordx4 v[218:219], off
	s_barrier
	s_waitcnt lgkmcnt(0)
	s_waitcnt lgkmcnt(0)
	v_mfma_f32_16x16x32_bf16 v[116:119], v[202:205], v[170:173], v[116:119]
	v_mfma_f32_16x16x32_bf16 v[112:115], v[210:213], v[170:173], v[112:115]
	v_mfma_f32_16x16x32_bf16 v[100:103], v[202:205], v[178:181], v[100:103]
	v_mfma_f32_16x16x32_bf16 v[96:99], v[210:213], v[178:181], v[96:99]
	v_mfma_f32_16x16x32_bf16 v[84:87], v[202:205], v[186:189], v[84:87]
	v_mfma_f32_16x16x32_bf16 v[80:83], v[210:213], v[186:189], v[80:83]
	v_mfma_f32_16x16x32_bf16 v[68:71], v[202:205], v[194:197], v[68:71]
	v_mfma_f32_16x16x32_bf16 v[64:67], v[210:213], v[194:197], v[64:67]
	v_mfma_f32_16x16x32_bf16 v[116:119], v[206:209], v[174:177], v[116:119]
	v_mfma_f32_16x16x32_bf16 v[112:115], v[214:217], v[174:177], v[112:115]
	v_mfma_f32_16x16x32_bf16 v[100:103], v[206:209], v[182:185], v[100:103]
	v_mfma_f32_16x16x32_bf16 v[96:99], v[214:217], v[182:185], v[96:99]
	v_mfma_f32_16x16x32_bf16 v[84:87], v[206:209], v[190:193], v[84:87]
	v_mfma_f32_16x16x32_bf16 v[80:83], v[214:217], v[190:193], v[80:83]
	v_mfma_f32_16x16x32_bf16 v[68:71], v[206:209], v[198:201], v[68:71]
	v_mfma_f32_16x16x32_bf16 v[64:67], v[214:217], v[198:201], v[64:67]
	s_mov_b32 m0, s71
	v_lshl_add_u64 v[218:219], v[222:223], 0, s[8:9]
	s_barrier
	ds_read_b128 v[170:173], v152 offset:49152
	ds_read_b128 v[174:177], v152 offset:50176
	ds_read_b128 v[178:181], v152 offset:51200
	ds_read_b128 v[182:185], v152 offset:52224
	ds_read_b128 v[186:189], v152 offset:53248
	ds_read_b128 v[190:193], v152 offset:54272
	ds_read_b128 v[194:197], v152 offset:55296
	ds_read_b128 v[198:201], v152 offset:56320
	global_load_lds_dwordx4 v[218:219], off
	v_lshl_add_u64 v[218:219], v[224:225], 0, s[8:9]
	s_mov_b32 m0, s72
	s_nop 0
	global_load_lds_dwordx4 v[218:219], off
	s_barrier
	s_waitcnt lgkmcnt(0)
	s_waitcnt lgkmcnt(0)
	v_mfma_f32_16x16x32_bf16 v[60:63], v[154:157], v[170:173], v[60:63]
	v_mfma_f32_16x16x32_bf16 v[56:59], v[162:165], v[170:173], v[56:59]
	v_mfma_f32_16x16x32_bf16 v[44:47], v[154:157], v[178:181], v[44:47]
	v_mfma_f32_16x16x32_bf16 v[40:43], v[162:165], v[178:181], v[40:43]
	v_mfma_f32_16x16x32_bf16 v[28:31], v[154:157], v[186:189], v[28:31]
	v_mfma_f32_16x16x32_bf16 v[24:27], v[162:165], v[186:189], v[24:27]
	v_mfma_f32_16x16x32_bf16 v[12:15], v[154:157], v[194:197], v[12:15]
	v_mfma_f32_16x16x32_bf16 v[8:11], v[162:165], v[194:197], v[8:11]
	v_mfma_f32_16x16x32_bf16 v[60:63], v[158:161], v[174:177], v[60:63]
	v_mfma_f32_16x16x32_bf16 v[56:59], v[166:169], v[174:177], v[56:59]
	v_mfma_f32_16x16x32_bf16 v[44:47], v[158:161], v[182:185], v[44:47]
	v_mfma_f32_16x16x32_bf16 v[40:43], v[166:169], v[182:185], v[40:43]
	v_mfma_f32_16x16x32_bf16 v[28:31], v[158:161], v[190:193], v[28:31]
	v_mfma_f32_16x16x32_bf16 v[24:27], v[166:169], v[190:193], v[24:27]
	v_mfma_f32_16x16x32_bf16 v[12:15], v[158:161], v[198:201], v[12:15]
	v_mfma_f32_16x16x32_bf16 v[8:11], v[166:169], v[198:201], v[8:11]
	s_barrier
	s_add_u32 s34, s34, 0x40080
	s_addc_u32 s35, s35, 0
	s_add_i32 s54, s54, s60
	v_lshl_add_u64 v[154:155], s[34:35], 0, v[132:133]
	s_mov_b32 m0, s54
	s_nop 0
	global_load_lds_dwordx4 v[154:155], off
	v_lshl_add_u64 v[154:155], s[34:35], 0, v[136:137]
	s_add_i32 m0, s54, 0x2000
	s_nop 0
	global_load_lds_dwordx4 v[154:155], off
	s_waitcnt vmcnt(6)
	s_barrier
	v_mfma_f32_16x16x32_bf16 v[52:55], v[202:205], v[170:173], v[52:55]
	v_mfma_f32_16x16x32_bf16 v[48:51], v[210:213], v[170:173], v[48:51]
	v_mfma_f32_16x16x32_bf16 v[36:39], v[202:205], v[178:181], v[36:39]
	v_mfma_f32_16x16x32_bf16 v[32:35], v[210:213], v[178:181], v[32:35]
	v_mfma_f32_16x16x32_bf16 v[20:23], v[202:205], v[186:189], v[20:23]
	v_mfma_f32_16x16x32_bf16 v[16:19], v[210:213], v[186:189], v[16:19]
	v_mfma_f32_16x16x32_bf16 v[4:7], v[202:205], v[194:197], v[4:7]
	v_mfma_f32_16x16x32_bf16 v[0:3], v[210:213], v[194:197], v[0:3]
	v_mfma_f32_16x16x32_bf16 v[52:55], v[206:209], v[174:177], v[52:55]
	v_mfma_f32_16x16x32_bf16 v[48:51], v[214:217], v[174:177], v[48:51]
	v_mfma_f32_16x16x32_bf16 v[36:39], v[206:209], v[182:185], v[36:39]
	v_mfma_f32_16x16x32_bf16 v[32:35], v[214:217], v[182:185], v[32:35]
	v_mfma_f32_16x16x32_bf16 v[20:23], v[206:209], v[190:193], v[20:23]
	v_mfma_f32_16x16x32_bf16 v[16:19], v[214:217], v[190:193], v[16:19]
	v_mfma_f32_16x16x32_bf16 v[4:7], v[206:209], v[198:201], v[4:7]
	v_mfma_f32_16x16x32_bf16 v[0:3], v[214:217], v[198:201], v[0:3]
	s_add_i32 s85, s85, 2
	s_add_u32 s30, s30, 0x100
	s_addc_u32 s31, s31, 0
	s_add_u32 s83, s83, 0x100
	s_addc_u32 s84, s84, 0
	s_cmp_gt_u32 s85, 13
	s_barrier
	s_cbranch_scc0 .LBB0_683
	v_lshl_add_u32 v154, s28, 8, v148
	v_lshl_or_b32 v156, s80, 8, v150
	v_ashrrev_i32_e32 v155, 31, v154
	v_max_f32_e32 v126, 0, v126
	v_max_f32_e32 v127, 0, v127
	v_lshlrev_b64 v[158:159], 13, v[154:155]
	v_max_f32_e32 v124, 0, v124
	v_max_f32_e32 v120, 0, v120
	v_max_f32_e32 v125, 0, v125
	v_max_f32_e32 v121, 0, v121
	v_max_f32_e32 v122, 0, v122
	v_max_f32_e32 v123, 0, v123
	v_pk_mul_f32 v[126:127], v[126:127], v[126:127]
	v_ashrrev_i32_e32 v157, 31, v156
	v_lshl_add_u64 v[158:159], s[46:47], 0, v[158:159]
	v_pk_mul_f32 v[124:125], v[124:125], v[124:125]
	v_pk_mul_f32 v[120:121], v[120:121], v[120:121]
	v_pk_mul_f32 v[160:161], v[122:123], v[122:123]
	v_cvt_pk_bf16_f32 v123, v126, v127
	v_lshlrev_b64 v[126:127], 1, v[156:157]
	v_cvt_pk_bf16_f32 v122, v124, v125
	v_cvt_pk_bf16_f32 v124, v120, v121
	v_cvt_pk_bf16_f32 v125, v160, v161
	v_lshl_add_u64 v[120:121], v[158:159], 0, v[126:127]
	v_max_f32_e32 v112, 0, v112
	v_max_f32_e32 v113, 0, v113
	global_store_dwordx4 v[120:121], v[122:125], off
	s_nop 1
	v_pk_mul_f32 v[122:123], v[112:113], v[112:113]
	v_max_f32_e32 v113, v114, v114
	v_max_f32_e32 v112, v118, v118
	v_max_f32_e32 v114, 0, v113
	v_max_f32_e32 v113, v119, v119
	v_max_f32_e32 v116, 0, v116
	v_max_f32_e32 v117, 0, v117
	v_max_f32_e32 v112, 0, v112
	v_max_f32_e32 v113, 0, v113
	v_max_f32_e32 v115, 0, v115
	v_pk_mul_f32 v[116:117], v[116:117], v[116:117]
	v_pk_mul_f32 v[118:119], v[112:113], v[112:113]
	v_pk_mul_f32 v[124:125], v[114:115], v[114:115]
	v_cvt_pk_bf16_f32 v112, v116, v117
	v_cvt_pk_bf16_f32 v113, v118, v119
	v_cvt_pk_bf16_f32 v114, v122, v123
	v_cvt_pk_bf16_f32 v115, v124, v125
	v_max_f32_e32 v104, 0, v104
	v_max_f32_e32 v105, 0, v105
	global_store_dwordx4 v[120:121], v[112:115], off offset:256
	s_nop 1
	v_or_b32_e32 v112, 16, v154
	v_pk_mul_f32 v[114:115], v[104:105], v[104:105]
	v_max_f32_e32 v105, v106, v106
	v_ashrrev_i32_e32 v113, 31, v112
	v_max_f32_e32 v104, v110, v110
	v_max_f32_e32 v106, 0, v105
	v_max_f32_e32 v105, v111, v111
	v_lshlrev_b64 v[112:113], 13, v[112:113]
	v_max_f32_e32 v108, 0, v108
	v_max_f32_e32 v109, 0, v109
	v_max_f32_e32 v104, 0, v104
	v_max_f32_e32 v105, 0, v105
	v_max_f32_e32 v107, 0, v107
	v_lshl_add_u64 v[112:113], s[46:47], 0, v[112:113]
	v_pk_mul_f32 v[108:109], v[108:109], v[108:109]
	v_pk_mul_f32 v[110:111], v[104:105], v[104:105]
	v_pk_mul_f32 v[116:117], v[106:107], v[106:107]
	v_cvt_pk_bf16_f32 v104, v108, v109
	v_cvt_pk_bf16_f32 v105, v110, v111
	v_cvt_pk_bf16_f32 v106, v114, v115
	v_cvt_pk_bf16_f32 v107, v116, v117
	v_lshl_add_u64 v[108:109], v[112:113], 0, v[126:127]
	v_max_f32_e32 v96, 0, v96
	v_max_f32_e32 v97, 0, v97
	global_store_dwordx4 v[108:109], v[104:107], off
	s_nop 1
	v_pk_mul_f32 v[104:105], v[96:97], v[96:97]
	v_max_f32_e32 v97, v98, v98
	v_max_f32_e32 v96, v102, v102
	v_max_f32_e32 v98, 0, v97
	v_max_f32_e32 v97, v103, v103
	v_max_f32_e32 v100, 0, v100
	v_max_f32_e32 v101, 0, v101
	v_max_f32_e32 v96, 0, v96
	v_max_f32_e32 v97, 0, v97
	v_max_f32_e32 v99, 0, v99
	v_pk_mul_f32 v[100:101], v[100:101], v[100:101]
	v_pk_mul_f32 v[102:103], v[96:97], v[96:97]
	v_pk_mul_f32 v[106:107], v[98:99], v[98:99]
	v_cvt_pk_bf16_f32 v96, v100, v101
	v_cvt_pk_bf16_f32 v97, v102, v103
	v_cvt_pk_bf16_f32 v98, v104, v105
	v_cvt_pk_bf16_f32 v99, v106, v107
	v_max_f32_e32 v88, 0, v88
	v_max_f32_e32 v89, 0, v89
	global_store_dwordx4 v[108:109], v[96:99], off offset:256
	s_nop 1
	v_or_b32_e32 v96, 32, v154
	v_pk_mul_f32 v[98:99], v[88:89], v[88:89]
	v_max_f32_e32 v89, v90, v90
	v_ashrrev_i32_e32 v97, 31, v96
	v_max_f32_e32 v88, v94, v94
	v_max_f32_e32 v90, 0, v89
	v_max_f32_e32 v89, v95, v95
	v_lshlrev_b64 v[96:97], 13, v[96:97]
	v_max_f32_e32 v92, 0, v92
	v_max_f32_e32 v93, 0, v93
	v_max_f32_e32 v88, 0, v88
	v_max_f32_e32 v89, 0, v89
	v_max_f32_e32 v91, 0, v91
	v_lshl_add_u64 v[96:97], s[46:47], 0, v[96:97]
	v_pk_mul_f32 v[92:93], v[92:93], v[92:93]
	v_pk_mul_f32 v[94:95], v[88:89], v[88:89]
	v_pk_mul_f32 v[100:101], v[90:91], v[90:91]
	v_cvt_pk_bf16_f32 v88, v92, v93
	v_cvt_pk_bf16_f32 v89, v94, v95
	v_cvt_pk_bf16_f32 v90, v98, v99
	v_cvt_pk_bf16_f32 v91, v100, v101
	v_lshl_add_u64 v[92:93], v[96:97], 0, v[126:127]
	v_max_f32_e32 v80, 0, v80
	v_max_f32_e32 v81, 0, v81
	global_store_dwordx4 v[92:93], v[88:91], off
	s_nop 1
	v_pk_mul_f32 v[88:89], v[80:81], v[80:81]
	v_max_f32_e32 v81, v82, v82
	v_max_f32_e32 v80, v86, v86
	v_max_f32_e32 v82, 0, v81
	v_max_f32_e32 v81, v87, v87
	v_max_f32_e32 v84, 0, v84
	v_max_f32_e32 v85, 0, v85
	v_max_f32_e32 v80, 0, v80
	v_max_f32_e32 v81, 0, v81
	v_max_f32_e32 v83, 0, v83
	v_pk_mul_f32 v[84:85], v[84:85], v[84:85]
	v_pk_mul_f32 v[86:87], v[80:81], v[80:81]
	v_pk_mul_f32 v[90:91], v[82:83], v[82:83]
	v_cvt_pk_bf16_f32 v80, v84, v85
	v_cvt_pk_bf16_f32 v81, v86, v87
	v_cvt_pk_bf16_f32 v82, v88, v89
	v_cvt_pk_bf16_f32 v83, v90, v91
	v_max_f32_e32 v72, 0, v72
	v_max_f32_e32 v73, 0, v73
	global_store_dwordx4 v[92:93], v[80:83], off offset:256
	s_nop 1
	v_or_b32_e32 v80, 48, v154
	v_pk_mul_f32 v[82:83], v[72:73], v[72:73]
	v_max_f32_e32 v73, v74, v74
	v_ashrrev_i32_e32 v81, 31, v80
	v_max_f32_e32 v72, v78, v78
	v_max_f32_e32 v74, 0, v73
	v_max_f32_e32 v73, v79, v79
	v_lshlrev_b64 v[80:81], 13, v[80:81]
	v_max_f32_e32 v76, 0, v76
	v_max_f32_e32 v77, 0, v77
	v_max_f32_e32 v72, 0, v72
	v_max_f32_e32 v73, 0, v73
	v_max_f32_e32 v75, 0, v75
	v_lshl_add_u64 v[80:81], s[46:47], 0, v[80:81]
	v_pk_mul_f32 v[76:77], v[76:77], v[76:77]
	v_pk_mul_f32 v[78:79], v[72:73], v[72:73]
	v_pk_mul_f32 v[84:85], v[74:75], v[74:75]
	v_cvt_pk_bf16_f32 v72, v76, v77
	v_cvt_pk_bf16_f32 v73, v78, v79
	v_cvt_pk_bf16_f32 v74, v82, v83
	v_cvt_pk_bf16_f32 v75, v84, v85
	v_lshl_add_u64 v[76:77], v[80:81], 0, v[126:127]
	v_max_f32_e32 v64, 0, v64
	v_max_f32_e32 v65, 0, v65
	global_store_dwordx4 v[76:77], v[72:75], off
	s_nop 1
	v_pk_mul_f32 v[72:73], v[64:65], v[64:65]
	v_max_f32_e32 v65, v66, v66
	v_max_f32_e32 v64, v70, v70
	v_max_f32_e32 v66, 0, v65
	v_max_f32_e32 v65, v71, v71
	v_max_f32_e32 v68, 0, v68
	v_max_f32_e32 v69, 0, v69
	v_max_f32_e32 v64, 0, v64
	v_max_f32_e32 v65, 0, v65
	v_max_f32_e32 v67, 0, v67
	v_pk_mul_f32 v[68:69], v[68:69], v[68:69]
	v_pk_mul_f32 v[70:71], v[64:65], v[64:65]
	v_pk_mul_f32 v[74:75], v[66:67], v[66:67]
	v_cvt_pk_bf16_f32 v64, v68, v69
	v_cvt_pk_bf16_f32 v65, v70, v71
	v_cvt_pk_bf16_f32 v66, v72, v73
	v_cvt_pk_bf16_f32 v67, v74, v75
	v_max_f32_e32 v56, 0, v56
	v_max_f32_e32 v57, 0, v57
	global_store_dwordx4 v[76:77], v[64:67], off offset:256
	s_nop 1
	v_pk_mul_f32 v[64:65], v[56:57], v[56:57]
	v_max_f32_e32 v57, v58, v58
	v_max_f32_e32 v56, v62, v62
	v_max_f32_e32 v58, 0, v57
	v_max_f32_e32 v57, v63, v63
	v_max_f32_e32 v56, 0, v56
	v_max_f32_e32 v57, 0, v57
	v_max_f32_e32 v60, 0, v60
	v_max_f32_e32 v61, 0, v61
	v_max_f32_e32 v59, 0, v59
	v_pk_mul_f32 v[62:63], v[56:57], v[56:57]
	v_pk_mul_f32 v[60:61], v[60:61], v[60:61]
	v_pk_mul_f32 v[66:67], v[58:59], v[58:59]
	v_cvt_pk_bf16_f32 v57, v62, v63
	v_add_co_u32_e32 v62, vcc, s76, v120
	v_cvt_pk_bf16_f32 v56, v60, v61
	v_cvt_pk_bf16_f32 v58, v64, v65
	v_cvt_pk_bf16_f32 v59, v66, v67
	v_addc_co_u32_e32 v63, vcc, 0, v121, vcc
	v_max_f32_e32 v48, 0, v48
	v_max_f32_e32 v49, 0, v49
	global_store_dwordx4 v[62:63], v[56:59], off
	s_nop 1
	v_pk_mul_f32 v[56:57], v[48:49], v[48:49]
	v_max_f32_e32 v49, v50, v50
	v_max_f32_e32 v48, v54, v54
	v_max_f32_e32 v50, 0, v49
	v_max_f32_e32 v49, v55, v55
	v_max_f32_e32 v52, 0, v52
	v_max_f32_e32 v53, 0, v53
	v_max_f32_e32 v48, 0, v48
	v_max_f32_e32 v49, 0, v49
	v_max_f32_e32 v51, 0, v51
	s_mov_b64 s[30:31], 0x100000
	v_pk_mul_f32 v[52:53], v[52:53], v[52:53]
	v_pk_mul_f32 v[54:55], v[48:49], v[48:49]
	v_pk_mul_f32 v[58:59], v[50:51], v[50:51]
	v_lshl_add_u64 v[60:61], v[120:121], 0, s[30:31]
	v_cvt_pk_bf16_f32 v48, v52, v53
	v_cvt_pk_bf16_f32 v49, v54, v55
	v_cvt_pk_bf16_f32 v50, v56, v57
	v_cvt_pk_bf16_f32 v51, v58, v59
	v_max_f32_e32 v40, 0, v40
	v_max_f32_e32 v41, 0, v41
	global_store_dwordx4 v[60:61], v[48:51], off offset:256
	s_nop 1
	v_pk_mul_f32 v[48:49], v[40:41], v[40:41]
	v_max_f32_e32 v41, v42, v42
	v_max_f32_e32 v40, v46, v46
	v_max_f32_e32 v42, 0, v41
	v_max_f32_e32 v41, v47, v47
	v_max_f32_e32 v40, 0, v40
	v_max_f32_e32 v41, 0, v41
	v_max_f32_e32 v44, 0, v44
	v_max_f32_e32 v45, 0, v45
	v_max_f32_e32 v43, 0, v43
	v_pk_mul_f32 v[46:47], v[40:41], v[40:41]
	v_pk_mul_f32 v[44:45], v[44:45], v[44:45]
	v_pk_mul_f32 v[50:51], v[42:43], v[42:43]
	v_cvt_pk_bf16_f32 v41, v46, v47
	v_add_co_u32_e32 v46, vcc, s77, v120
	v_cvt_pk_bf16_f32 v40, v44, v45
	v_cvt_pk_bf16_f32 v42, v48, v49
	v_cvt_pk_bf16_f32 v43, v50, v51
	v_addc_co_u32_e32 v47, vcc, 0, v121, vcc
	v_max_f32_e32 v32, 0, v32
	v_max_f32_e32 v33, 0, v33
	global_store_dwordx4 v[46:47], v[40:43], off
	s_nop 1
	v_pk_mul_f32 v[40:41], v[32:33], v[32:33]
	v_max_f32_e32 v33, v34, v34
	v_max_f32_e32 v32, v38, v38
	v_max_f32_e32 v34, 0, v33
	v_max_f32_e32 v33, v39, v39
	v_max_f32_e32 v36, 0, v36
	v_max_f32_e32 v37, 0, v37
	v_max_f32_e32 v32, 0, v32
	v_max_f32_e32 v33, 0, v33
	v_max_f32_e32 v35, 0, v35
	v_pk_mul_f32 v[36:37], v[36:37], v[36:37]
	v_pk_mul_f32 v[38:39], v[32:33], v[32:33]
	v_pk_mul_f32 v[42:43], v[34:35], v[34:35]
	v_lshl_add_u64 v[44:45], v[120:121], 0, s[10:11]
	v_cvt_pk_bf16_f32 v32, v36, v37
	v_cvt_pk_bf16_f32 v33, v38, v39
	v_cvt_pk_bf16_f32 v34, v40, v41
	v_cvt_pk_bf16_f32 v35, v42, v43
	v_max_f32_e32 v24, 0, v24
	v_max_f32_e32 v25, 0, v25
	global_store_dwordx4 v[44:45], v[32:35], off offset:256
	s_nop 1
	v_pk_mul_f32 v[32:33], v[24:25], v[24:25]
	v_max_f32_e32 v25, v26, v26
	v_max_f32_e32 v24, v30, v30
	v_max_f32_e32 v26, 0, v25
	v_max_f32_e32 v25, v31, v31
	v_max_f32_e32 v24, 0, v24
	v_max_f32_e32 v25, 0, v25
	v_max_f32_e32 v28, 0, v28
	v_max_f32_e32 v29, 0, v29
	v_max_f32_e32 v27, 0, v27
	v_pk_mul_f32 v[30:31], v[24:25], v[24:25]
	v_pk_mul_f32 v[28:29], v[28:29], v[28:29]
	v_pk_mul_f32 v[34:35], v[26:27], v[26:27]
	v_cvt_pk_bf16_f32 v25, v30, v31
	v_add_co_u32_e32 v30, vcc, s78, v120
	v_cvt_pk_bf16_f32 v24, v28, v29
	v_cvt_pk_bf16_f32 v26, v32, v33
	v_cvt_pk_bf16_f32 v27, v34, v35
	v_addc_co_u32_e32 v31, vcc, 0, v121, vcc
	v_max_f32_e32 v16, 0, v16
	v_max_f32_e32 v17, 0, v17
	global_store_dwordx4 v[30:31], v[24:27], off
	s_nop 1
	v_pk_mul_f32 v[24:25], v[16:17], v[16:17]
	v_max_f32_e32 v17, v18, v18
	v_max_f32_e32 v16, v22, v22
	v_max_f32_e32 v18, 0, v17
	v_max_f32_e32 v17, v23, v23
	v_max_f32_e32 v20, 0, v20
	v_max_f32_e32 v21, 0, v21
	v_max_f32_e32 v16, 0, v16
	v_max_f32_e32 v17, 0, v17
	v_max_f32_e32 v19, 0, v19
	v_pk_mul_f32 v[20:21], v[20:21], v[20:21]
	v_pk_mul_f32 v[22:23], v[16:17], v[16:17]
	v_pk_mul_f32 v[26:27], v[18:19], v[18:19]
	v_lshl_add_u64 v[28:29], v[120:121], 0, s[12:13]
	v_cvt_pk_bf16_f32 v16, v20, v21
	v_cvt_pk_bf16_f32 v17, v22, v23
	v_cvt_pk_bf16_f32 v18, v24, v25
	v_cvt_pk_bf16_f32 v19, v26, v27
	v_max_f32_e32 v8, 0, v8
	v_max_f32_e32 v9, 0, v9
	global_store_dwordx4 v[28:29], v[16:19], off offset:256
	s_nop 1
	v_pk_mul_f32 v[16:17], v[8:9], v[8:9]
	v_max_f32_e32 v9, v10, v10
	v_max_f32_e32 v8, v14, v14
	v_max_f32_e32 v10, 0, v9
	v_max_f32_e32 v9, v15, v15
	v_max_f32_e32 v8, 0, v8
	v_max_f32_e32 v9, 0, v9
	v_max_f32_e32 v12, 0, v12
	v_max_f32_e32 v13, 0, v13
	v_max_f32_e32 v11, 0, v11
	v_pk_mul_f32 v[14:15], v[8:9], v[8:9]
	v_pk_mul_f32 v[12:13], v[12:13], v[12:13]
	v_pk_mul_f32 v[18:19], v[10:11], v[10:11]
	v_cvt_pk_bf16_f32 v9, v14, v15
	v_add_co_u32_e32 v14, vcc, s79, v120
	v_cvt_pk_bf16_f32 v8, v12, v13
	v_cvt_pk_bf16_f32 v10, v16, v17
	v_cvt_pk_bf16_f32 v11, v18, v19
	v_addc_co_u32_e32 v15, vcc, 0, v121, vcc
	v_max_f32_e32 v0, 0, v0
	v_max_f32_e32 v1, 0, v1
	global_store_dwordx4 v[14:15], v[8:11], off
	s_nop 1
	v_pk_mul_f32 v[8:9], v[0:1], v[0:1]
	v_max_f32_e32 v1, v2, v2
	v_max_f32_e32 v0, v6, v6
	v_max_f32_e32 v2, 0, v1
	v_max_f32_e32 v1, v7, v7
	v_max_f32_e32 v4, 0, v4
	v_max_f32_e32 v5, 0, v5
	v_max_f32_e32 v0, 0, v0
	v_max_f32_e32 v1, 0, v1
	v_max_f32_e32 v3, 0, v3
	v_pk_mul_f32 v[4:5], v[4:5], v[4:5]
	v_pk_mul_f32 v[6:7], v[0:1], v[0:1]
	v_pk_mul_f32 v[10:11], v[2:3], v[2:3]
	v_lshl_add_u64 v[12:13], v[120:121], 0, s[14:15]
	v_cvt_pk_bf16_f32 v0, v4, v5
	v_cvt_pk_bf16_f32 v1, v6, v7
	v_cvt_pk_bf16_f32 v2, v8, v9
	v_cvt_pk_bf16_f32 v3, v10, v11
	s_and_b64 vcc, exec, s[4:5]
	s_mov_b32 s80, s16
	s_mov_b32 s28, s18
	s_mov_b64 s[34:35], s[26:27]
	s_mov_b64 s[30:31], s[20:21]
	global_store_dwordx4 v[12:13], v[0:3], off offset:256
	s_cbranch_vccz .LBB0_676
	s_waitcnt vmcnt(16)
	s_cmpk_gt_u32 s56, 0xff
	s_cbranch_scc1 .LBB0_687
	s_barrier

.LBB0_1291:
	ds_read_b128 v[154:157], v151
	ds_read_b128 v[158:161], v151 offset:1024
	ds_read_b128 v[162:165], v151 offset:2048
	ds_read_b128 v[166:169], v151 offset:3072
	s_add_u32 s36, s34, 0xfffc0080
	s_addc_u32 s37, s35, -1
	s_cmp_eq_u32 s79, 12
	s_cselect_b32 s39, s21, s37
	s_cselect_b32 s38, s75, s36
	s_cselect_b32 s37, s19, s78
	s_cselect_b32 s36, s76, s77
	v_lshl_add_u64 v[202:203], s[34:35], 0, v[138:139]
	s_add_i32 m0, s31, 0xc000
	ds_read_b128 v[170:173], v152
	ds_read_b128 v[174:177], v152 offset:1024
	ds_read_b128 v[178:181], v152 offset:2048
	ds_read_b128 v[182:185], v152 offset:3072
	ds_read_b128 v[186:189], v152 offset:4096
	ds_read_b128 v[190:193], v152 offset:5120
	ds_read_b128 v[194:197], v152 offset:6144
	ds_read_b128 v[198:201], v152 offset:7168
	global_load_lds_dwordx4 v[202:203], off
	v_lshl_add_u64 v[202:203], s[34:35], 0, v[140:141]
	s_add_i32 m0, s31, 0xe000
	s_nop 0
	global_load_lds_dwordx4 v[202:203], off
	s_waitcnt lgkmcnt(8)
	s_barrier
	s_waitcnt lgkmcnt(0)
	s_waitcnt lgkmcnt(0)
	v_mfma_f32_16x16x32_bf16 v[124:127], v[154:157], v[170:173], v[124:127]
	v_mfma_f32_16x16x32_bf16 v[120:123], v[162:165], v[170:173], v[120:123]
	v_mfma_f32_16x16x32_bf16 v[108:111], v[154:157], v[178:181], v[108:111]
	v_mfma_f32_16x16x32_bf16 v[104:107], v[162:165], v[178:181], v[104:107]
	v_mfma_f32_16x16x32_bf16 v[92:95], v[154:157], v[186:189], v[92:95]
	v_mfma_f32_16x16x32_bf16 v[88:91], v[162:165], v[186:189], v[88:91]
	v_mfma_f32_16x16x32_bf16 v[76:79], v[154:157], v[194:197], v[76:79]
	v_mfma_f32_16x16x32_bf16 v[72:75], v[162:165], v[194:197], v[72:75]
	v_mfma_f32_16x16x32_bf16 v[124:127], v[158:161], v[174:177], v[124:127]
	v_mfma_f32_16x16x32_bf16 v[120:123], v[166:169], v[174:177], v[120:123]
	v_mfma_f32_16x16x32_bf16 v[108:111], v[158:161], v[182:185], v[108:111]
	v_mfma_f32_16x16x32_bf16 v[104:107], v[166:169], v[182:185], v[104:107]
	v_mfma_f32_16x16x32_bf16 v[92:95], v[158:161], v[190:193], v[92:95]
	v_mfma_f32_16x16x32_bf16 v[88:91], v[166:169], v[190:193], v[88:91]
	v_mfma_f32_16x16x32_bf16 v[76:79], v[158:161], v[198:201], v[76:79]
	v_mfma_f32_16x16x32_bf16 v[72:75], v[166:169], v[198:201], v[72:75]
	s_barrier
	s_add_i32 s80, s62, s52
	v_lshl_add_u64 v[218:219], s[36:37], 0, v[132:133]
	s_mov_b32 m0, s80
	ds_read_b128 v[202:205], v153
	ds_read_b128 v[206:209], v153 offset:1024
	ds_read_b128 v[210:213], v153 offset:2048
	ds_read_b128 v[214:217], v153 offset:3072
	global_load_lds_dwordx4 v[218:219], off
	v_lshl_add_u64 v[220:221], s[36:37], 0, v[136:137]
	s_add_i32 m0, s80, 0x2000
	s_nop 0
	global_load_lds_dwordx4 v[220:221], off
	s_barrier
	s_waitcnt lgkmcnt(0)
	s_waitcnt lgkmcnt(0)
	v_mfma_f32_16x16x32_bf16 v[116:119], v[202:205], v[170:173], v[116:119]
	v_mfma_f32_16x16x32_bf16 v[112:115], v[210:213], v[170:173], v[112:115]
	v_mfma_f32_16x16x32_bf16 v[100:103], v[202:205], v[178:181], v[100:103]
	v_mfma_f32_16x16x32_bf16 v[96:99], v[210:213], v[178:181], v[96:99]
	v_mfma_f32_16x16x32_bf16 v[84:87], v[202:205], v[186:189], v[84:87]
	v_mfma_f32_16x16x32_bf16 v[80:83], v[210:213], v[186:189], v[80:83]
	v_mfma_f32_16x16x32_bf16 v[68:71], v[202:205], v[194:197], v[68:71]
	v_mfma_f32_16x16x32_bf16 v[64:67], v[210:213], v[194:197], v[64:67]
	v_mfma_f32_16x16x32_bf16 v[116:119], v[206:209], v[174:177], v[116:119]
	v_mfma_f32_16x16x32_bf16 v[112:115], v[214:217], v[174:177], v[112:115]
	v_mfma_f32_16x16x32_bf16 v[100:103], v[206:209], v[182:185], v[100:103]
	v_mfma_f32_16x16x32_bf16 v[96:99], v[214:217], v[182:185], v[96:99]
	v_mfma_f32_16x16x32_bf16 v[84:87], v[206:209], v[190:193], v[84:87]
	v_mfma_f32_16x16x32_bf16 v[80:83], v[214:217], v[190:193], v[80:83]
	v_mfma_f32_16x16x32_bf16 v[68:71], v[206:209], v[198:201], v[68:71]
	v_mfma_f32_16x16x32_bf16 v[64:67], v[214:217], v[198:201], v[64:67]
	s_mov_b32 m0, s31
	v_lshl_add_u64 v[222:223], s[38:39], 0, v[130:131]
	s_barrier
	ds_read_b128 v[170:173], v152 offset:16384
	ds_read_b128 v[174:177], v152 offset:17408
	ds_read_b128 v[178:181], v152 offset:18432
	ds_read_b128 v[182:185], v152 offset:19456
	ds_read_b128 v[186:189], v152 offset:20480
	ds_read_b128 v[190:193], v152 offset:21504
	ds_read_b128 v[194:197], v152 offset:22528
	ds_read_b128 v[198:201], v152 offset:23552
	global_load_lds_dwordx4 v[222:223], off
	v_lshl_add_u64 v[224:225], s[38:39], 0, v[134:135]
	s_mov_b32 m0, s53
	s_nop 0
	global_load_lds_dwordx4 v[224:225], off
	s_barrier
	s_waitcnt lgkmcnt(0)
	s_waitcnt lgkmcnt(0)
	v_mfma_f32_16x16x32_bf16 v[60:63], v[154:157], v[170:173], v[60:63]
	v_mfma_f32_16x16x32_bf16 v[56:59], v[162:165], v[170:173], v[56:59]
	v_mfma_f32_16x16x32_bf16 v[44:47], v[154:157], v[178:181], v[44:47]
	v_mfma_f32_16x16x32_bf16 v[40:43], v[162:165], v[178:181], v[40:43]
	v_mfma_f32_16x16x32_bf16 v[28:31], v[154:157], v[186:189], v[28:31]
	v_mfma_f32_16x16x32_bf16 v[24:27], v[162:165], v[186:189], v[24:27]
	v_mfma_f32_16x16x32_bf16 v[12:15], v[154:157], v[194:197], v[12:15]
	v_mfma_f32_16x16x32_bf16 v[8:11], v[162:165], v[194:197], v[8:11]
	v_mfma_f32_16x16x32_bf16 v[60:63], v[158:161], v[174:177], v[60:63]
	v_mfma_f32_16x16x32_bf16 v[56:59], v[166:169], v[174:177], v[56:59]
	v_mfma_f32_16x16x32_bf16 v[44:47], v[158:161], v[182:185], v[44:47]
	v_mfma_f32_16x16x32_bf16 v[40:43], v[166:169], v[182:185], v[40:43]
	v_mfma_f32_16x16x32_bf16 v[28:31], v[158:161], v[190:193], v[28:31]
	v_mfma_f32_16x16x32_bf16 v[24:27], v[166:169], v[190:193], v[24:27]
	v_mfma_f32_16x16x32_bf16 v[12:15], v[158:161], v[198:201], v[12:15]
	v_mfma_f32_16x16x32_bf16 v[8:11], v[166:169], v[198:201], v[8:11]
	s_barrier
	s_add_u32 s80, s36, 0x40000
	s_addc_u32 s81, s37, 0
	s_add_i32 s82, s63, s52
	v_lshl_add_u64 v[154:155], s[80:81], 0, v[132:133]
	s_mov_b32 m0, s82
	s_nop 0
	global_load_lds_dwordx4 v[154:155], off
	v_lshl_add_u64 v[154:155], s[80:81], 0, v[136:137]
	s_add_i32 m0, s82, 0x2000
	s_nop 0
	global_load_lds_dwordx4 v[154:155], off
	s_waitcnt vmcnt(6)
	s_barrier
	v_mfma_f32_16x16x32_bf16 v[52:55], v[202:205], v[170:173], v[52:55]
	v_mfma_f32_16x16x32_bf16 v[48:51], v[210:213], v[170:173], v[48:51]
	v_mfma_f32_16x16x32_bf16 v[36:39], v[202:205], v[178:181], v[36:39]
	v_mfma_f32_16x16x32_bf16 v[32:35], v[210:213], v[178:181], v[32:35]
	v_mfma_f32_16x16x32_bf16 v[20:23], v[202:205], v[186:189], v[20:23]
	v_mfma_f32_16x16x32_bf16 v[16:19], v[210:213], v[186:189], v[16:19]
	v_mfma_f32_16x16x32_bf16 v[4:7], v[202:205], v[194:197], v[4:7]
	v_mfma_f32_16x16x32_bf16 v[0:3], v[210:213], v[194:197], v[0:3]
	v_mfma_f32_16x16x32_bf16 v[52:55], v[206:209], v[174:177], v[52:55]
	v_mfma_f32_16x16x32_bf16 v[48:51], v[214:217], v[174:177], v[48:51]
	v_mfma_f32_16x16x32_bf16 v[36:39], v[206:209], v[182:185], v[36:39]
	v_mfma_f32_16x16x32_bf16 v[32:35], v[214:217], v[182:185], v[32:35]
	v_mfma_f32_16x16x32_bf16 v[20:23], v[206:209], v[190:193], v[20:23]
	v_mfma_f32_16x16x32_bf16 v[16:19], v[214:217], v[190:193], v[16:19]
	v_mfma_f32_16x16x32_bf16 v[4:7], v[206:209], v[198:201], v[4:7]
	v_mfma_f32_16x16x32_bf16 v[0:3], v[214:217], v[198:201], v[0:3]
	s_add_i32 s80, 0, 0x18000
	v_add_u32_e32 v166, s80, v149
	s_barrier
	ds_read_b128 v[154:157], v166
	ds_read_b128 v[158:161], v166 offset:1024
	ds_read_b128 v[162:165], v166 offset:2048
	ds_read_b128 v[166:169], v166 offset:3072
	s_add_u32 s38, s38, 0x40000
	s_addc_u32 s39, s39, 0
	s_mov_b32 m0, s54
	v_lshl_add_u64 v[202:203], s[38:39], 0, v[130:131]
	ds_read_b128 v[170:173], v152 offset:32768
	ds_read_b128 v[174:177], v152 offset:33792
	ds_read_b128 v[178:181], v152 offset:34816
	ds_read_b128 v[182:185], v152 offset:35840
	ds_read_b128 v[186:189], v152 offset:36864
	ds_read_b128 v[190:193], v152 offset:37888
	ds_read_b128 v[194:197], v152 offset:38912
	ds_read_b128 v[198:201], v152 offset:39936
	global_load_lds_dwordx4 v[202:203], off
	v_lshl_add_u64 v[202:203], s[38:39], 0, v[134:135]
	s_mov_b32 m0, s55
	s_nop 0
	global_load_lds_dwordx4 v[202:203], off
	s_waitcnt lgkmcnt(8)
	s_barrier
	s_waitcnt lgkmcnt(0)
	s_waitcnt lgkmcnt(0)
	v_mfma_f32_16x16x32_bf16 v[124:127], v[154:157], v[170:173], v[124:127]
	v_mfma_f32_16x16x32_bf16 v[120:123], v[162:165], v[170:173], v[120:123]
	v_mfma_f32_16x16x32_bf16 v[108:111], v[154:157], v[178:181], v[108:111]
	v_mfma_f32_16x16x32_bf16 v[104:107], v[162:165], v[178:181], v[104:107]
	v_mfma_f32_16x16x32_bf16 v[92:95], v[154:157], v[186:189], v[92:95]
	v_mfma_f32_16x16x32_bf16 v[88:91], v[162:165], v[186:189], v[88:91]
	v_mfma_f32_16x16x32_bf16 v[76:79], v[154:157], v[194:197], v[76:79]
	v_mfma_f32_16x16x32_bf16 v[72:75], v[162:165], v[194:197], v[72:75]
	v_mfma_f32_16x16x32_bf16 v[124:127], v[158:161], v[174:177], v[124:127]
	v_mfma_f32_16x16x32_bf16 v[120:123], v[166:169], v[174:177], v[120:123]
	v_mfma_f32_16x16x32_bf16 v[108:111], v[158:161], v[182:185], v[108:111]
	v_mfma_f32_16x16x32_bf16 v[104:107], v[166:169], v[182:185], v[104:107]
	v_mfma_f32_16x16x32_bf16 v[92:95], v[158:161], v[190:193], v[92:95]
	v_mfma_f32_16x16x32_bf16 v[88:91], v[166:169], v[190:193], v[88:91]
	v_mfma_f32_16x16x32_bf16 v[76:79], v[158:161], v[198:201], v[76:79]
	v_mfma_f32_16x16x32_bf16 v[72:75], v[166:169], v[198:201], v[72:75]
	s_barrier
	s_add_i32 s38, 0, 0x1c000
	s_add_i32 s39, s80, s52
	v_add_u32_e32 v214, s38, v149
	v_lshl_add_u64 v[218:219], v[218:219], 0, s[8:9]
	s_mov_b32 m0, s39
	ds_read_b128 v[202:205], v214
	ds_read_b128 v[206:209], v214 offset:1024
	ds_read_b128 v[210:213], v214 offset:2048
	ds_read_b128 v[214:217], v214 offset:3072
	global_load_lds_dwordx4 v[218:219], off
	v_lshl_add_u64 v[218:219], v[220:221], 0, s[8:9]
	s_add_i32 m0, s39, 0x2000
	s_nop 0
	global_load_lds_dwordx4 v[218:219], off
	s_barrier
	s_waitcnt lgkmcnt(0)
	s_waitcnt lgkmcnt(0)
	v_mfma_f32_16x16x32_bf16 v[116:119], v[202:205], v[170:173], v[116:119]
	v_mfma_f32_16x16x32_bf16 v[112:115], v[210:213], v[170:173], v[112:115]
	v_mfma_f32_16x16x32_bf16 v[100:103], v[202:205], v[178:181], v[100:103]
	v_mfma_f32_16x16x32_bf16 v[96:99], v[210:213], v[178:181], v[96:99]
	v_mfma_f32_16x16x32_bf16 v[84:87], v[202:205], v[186:189], v[84:87]
	v_mfma_f32_16x16x32_bf16 v[80:83], v[210:213], v[186:189], v[80:83]
	v_mfma_f32_16x16x32_bf16 v[68:71], v[202:205], v[194:197], v[68:71]
	v_mfma_f32_16x16x32_bf16 v[64:67], v[210:213], v[194:197], v[64:67]
	v_mfma_f32_16x16x32_bf16 v[116:119], v[206:209], v[174:177], v[116:119]
	v_mfma_f32_16x16x32_bf16 v[112:115], v[214:217], v[174:177], v[112:115]
	v_mfma_f32_16x16x32_bf16 v[100:103], v[206:209], v[182:185], v[100:103]
	v_mfma_f32_16x16x32_bf16 v[96:99], v[214:217], v[182:185], v[96:99]
	v_mfma_f32_16x16x32_bf16 v[84:87], v[206:209], v[190:193], v[84:87]
	v_mfma_f32_16x16x32_bf16 v[80:83], v[214:217], v[190:193], v[80:83]
	v_mfma_f32_16x16x32_bf16 v[68:71], v[206:209], v[198:201], v[68:71]
	v_mfma_f32_16x16x32_bf16 v[64:67], v[214:217], v[198:201], v[64:67]
	s_mov_b32 m0, s57
	v_lshl_add_u64 v[218:219], v[222:223], 0, s[8:9]
	s_barrier
	ds_read_b128 v[170:173], v152 offset:49152
	ds_read_b128 v[174:177], v152 offset:50176
	ds_read_b128 v[178:181], v152 offset:51200
	ds_read_b128 v[182:185], v152 offset:52224
	ds_read_b128 v[186:189], v152 offset:53248
	ds_read_b128 v[190:193], v152 offset:54272
	ds_read_b128 v[194:197], v152 offset:55296
	ds_read_b128 v[198:201], v152 offset:56320
	global_load_lds_dwordx4 v[218:219], off
	v_lshl_add_u64 v[218:219], v[224:225], 0, s[8:9]
	s_mov_b32 m0, s60
	s_nop 0
	global_load_lds_dwordx4 v[218:219], off
	s_barrier
	s_waitcnt lgkmcnt(0)
	s_waitcnt lgkmcnt(0)
	v_mfma_f32_16x16x32_bf16 v[60:63], v[154:157], v[170:173], v[60:63]
	v_mfma_f32_16x16x32_bf16 v[56:59], v[162:165], v[170:173], v[56:59]
	v_mfma_f32_16x16x32_bf16 v[44:47], v[154:157], v[178:181], v[44:47]
	v_mfma_f32_16x16x32_bf16 v[40:43], v[162:165], v[178:181], v[40:43]
	v_mfma_f32_16x16x32_bf16 v[28:31], v[154:157], v[186:189], v[28:31]
	v_mfma_f32_16x16x32_bf16 v[24:27], v[162:165], v[186:189], v[24:27]
	v_mfma_f32_16x16x32_bf16 v[12:15], v[154:157], v[194:197], v[12:15]
	v_mfma_f32_16x16x32_bf16 v[8:11], v[162:165], v[194:197], v[8:11]
	v_mfma_f32_16x16x32_bf16 v[60:63], v[158:161], v[174:177], v[60:63]
	v_mfma_f32_16x16x32_bf16 v[56:59], v[166:169], v[174:177], v[56:59]
	v_mfma_f32_16x16x32_bf16 v[44:47], v[158:161], v[182:185], v[44:47]
	v_mfma_f32_16x16x32_bf16 v[40:43], v[166:169], v[182:185], v[40:43]
	v_mfma_f32_16x16x32_bf16 v[28:31], v[158:161], v[190:193], v[28:31]
	v_mfma_f32_16x16x32_bf16 v[24:27], v[166:169], v[190:193], v[24:27]
	v_mfma_f32_16x16x32_bf16 v[12:15], v[158:161], v[198:201], v[12:15]
	v_mfma_f32_16x16x32_bf16 v[8:11], v[166:169], v[198:201], v[8:11]
	s_barrier
	s_add_u32 s36, s36, 0x40080
	s_addc_u32 s37, s37, 0
	s_add_i32 s38, s38, s52
	v_lshl_add_u64 v[154:155], s[36:37], 0, v[132:133]
	s_mov_b32 m0, s38
	s_nop 0
	global_load_lds_dwordx4 v[154:155], off
	v_lshl_add_u64 v[154:155], s[36:37], 0, v[136:137]
	s_add_i32 m0, s38, 0x2000
	s_nop 0
	global_load_lds_dwordx4 v[154:155], off
	s_waitcnt vmcnt(6)
	s_barrier
	v_mfma_f32_16x16x32_bf16 v[52:55], v[202:205], v[170:173], v[52:55]
	v_mfma_f32_16x16x32_bf16 v[48:51], v[210:213], v[170:173], v[48:51]
	v_mfma_f32_16x16x32_bf16 v[36:39], v[202:205], v[178:181], v[36:39]
	v_mfma_f32_16x16x32_bf16 v[32:35], v[210:213], v[178:181], v[32:35]
	v_mfma_f32_16x16x32_bf16 v[20:23], v[202:205], v[186:189], v[20:23]
	v_mfma_f32_16x16x32_bf16 v[16:19], v[210:213], v[186:189], v[16:19]
	v_mfma_f32_16x16x32_bf16 v[4:7], v[202:205], v[194:197], v[4:7]
	v_mfma_f32_16x16x32_bf16 v[0:3], v[210:213], v[194:197], v[0:3]
	v_mfma_f32_16x16x32_bf16 v[52:55], v[206:209], v[174:177], v[52:55]
	v_mfma_f32_16x16x32_bf16 v[48:51], v[214:217], v[174:177], v[48:51]
	v_mfma_f32_16x16x32_bf16 v[36:39], v[206:209], v[182:185], v[36:39]
	v_mfma_f32_16x16x32_bf16 v[32:35], v[214:217], v[182:185], v[32:35]
	v_mfma_f32_16x16x32_bf16 v[20:23], v[206:209], v[190:193], v[20:23]
	v_mfma_f32_16x16x32_bf16 v[16:19], v[214:217], v[190:193], v[16:19]
	v_mfma_f32_16x16x32_bf16 v[4:7], v[206:209], v[198:201], v[4:7]
	v_mfma_f32_16x16x32_bf16 v[0:3], v[214:217], v[198:201], v[0:3]
	s_add_i32 s79, s79, 2
	s_add_u32 s34, s34, 0x100
	s_addc_u32 s35, s35, 0
	s_add_u32 s77, s77, 0x100
	s_addc_u32 s78, s78, 0
	s_cmp_gt_u32 s79, 13
	s_barrier
	s_cbranch_scc0 .LBB0_1291
	v_lshl_add_u32 v154, s30, 8, v148
	v_lshl_or_b32 v156, s74, 8, v150
	v_ashrrev_i32_e32 v155, 31, v154
	v_max_f32_e32 v126, 0, v126
	v_max_f32_e32 v127, 0, v127
	v_lshlrev_b64 v[158:159], 13, v[154:155]
	v_max_f32_e32 v124, 0, v124
	v_max_f32_e32 v120, 0, v120
	v_max_f32_e32 v125, 0, v125
	v_max_f32_e32 v121, 0, v121
	v_max_f32_e32 v122, 0, v122
	v_max_f32_e32 v123, 0, v123
	v_pk_mul_f32 v[126:127], v[126:127], v[126:127]
	v_ashrrev_i32_e32 v157, 31, v156
	v_lshl_add_u64 v[158:159], s[46:47], 0, v[158:159]
	v_pk_mul_f32 v[124:125], v[124:125], v[124:125]
	v_pk_mul_f32 v[120:121], v[120:121], v[120:121]
	v_pk_mul_f32 v[160:161], v[122:123], v[122:123]
	v_cvt_pk_bf16_f32 v123, v126, v127
	v_lshlrev_b64 v[126:127], 1, v[156:157]
	v_cvt_pk_bf16_f32 v122, v124, v125
	v_cvt_pk_bf16_f32 v124, v120, v121
	v_cvt_pk_bf16_f32 v125, v160, v161
	v_lshl_add_u64 v[120:121], v[158:159], 0, v[126:127]
	v_max_f32_e32 v112, 0, v112
	v_max_f32_e32 v113, 0, v113
	global_store_dwordx4 v[120:121], v[122:125], off
	s_nop 1
	v_pk_mul_f32 v[122:123], v[112:113], v[112:113]
	v_max_f32_e32 v113, v114, v114
	v_max_f32_e32 v112, v118, v118
	v_max_f32_e32 v114, 0, v113
	v_max_f32_e32 v113, v119, v119
	v_max_f32_e32 v116, 0, v116
	v_max_f32_e32 v117, 0, v117
	v_max_f32_e32 v112, 0, v112
	v_max_f32_e32 v113, 0, v113
	v_max_f32_e32 v115, 0, v115
	v_pk_mul_f32 v[116:117], v[116:117], v[116:117]
	v_pk_mul_f32 v[118:119], v[112:113], v[112:113]
	v_pk_mul_f32 v[124:125], v[114:115], v[114:115]
	v_cvt_pk_bf16_f32 v112, v116, v117
	v_cvt_pk_bf16_f32 v113, v118, v119
	v_cvt_pk_bf16_f32 v114, v122, v123
	v_cvt_pk_bf16_f32 v115, v124, v125
	v_max_f32_e32 v104, 0, v104
	v_max_f32_e32 v105, 0, v105
	global_store_dwordx4 v[120:121], v[112:115], off offset:256
	s_nop 1
	v_or_b32_e32 v112, 16, v154
	v_pk_mul_f32 v[114:115], v[104:105], v[104:105]
	v_max_f32_e32 v105, v106, v106
	v_ashrrev_i32_e32 v113, 31, v112
	v_max_f32_e32 v104, v110, v110
	v_max_f32_e32 v106, 0, v105
	v_max_f32_e32 v105, v111, v111
	v_lshlrev_b64 v[112:113], 13, v[112:113]
	v_max_f32_e32 v108, 0, v108
	v_max_f32_e32 v109, 0, v109
	v_max_f32_e32 v104, 0, v104
	v_max_f32_e32 v105, 0, v105
	v_max_f32_e32 v107, 0, v107
	v_lshl_add_u64 v[112:113], s[46:47], 0, v[112:113]
	v_pk_mul_f32 v[108:109], v[108:109], v[108:109]
	v_pk_mul_f32 v[110:111], v[104:105], v[104:105]
	v_pk_mul_f32 v[116:117], v[106:107], v[106:107]
	v_cvt_pk_bf16_f32 v104, v108, v109
	v_cvt_pk_bf16_f32 v105, v110, v111
	v_cvt_pk_bf16_f32 v106, v114, v115
	v_cvt_pk_bf16_f32 v107, v116, v117
	v_lshl_add_u64 v[108:109], v[112:113], 0, v[126:127]
	v_max_f32_e32 v96, 0, v96
	v_max_f32_e32 v97, 0, v97
	global_store_dwordx4 v[108:109], v[104:107], off
	s_nop 1
	v_pk_mul_f32 v[104:105], v[96:97], v[96:97]
	v_max_f32_e32 v97, v98, v98
	v_max_f32_e32 v96, v102, v102
	v_max_f32_e32 v98, 0, v97
	v_max_f32_e32 v97, v103, v103
	v_max_f32_e32 v100, 0, v100
	v_max_f32_e32 v101, 0, v101
	v_max_f32_e32 v96, 0, v96
	v_max_f32_e32 v97, 0, v97
	v_max_f32_e32 v99, 0, v99
	v_pk_mul_f32 v[100:101], v[100:101], v[100:101]
	v_pk_mul_f32 v[102:103], v[96:97], v[96:97]
	v_pk_mul_f32 v[106:107], v[98:99], v[98:99]
	v_cvt_pk_bf16_f32 v96, v100, v101
	v_cvt_pk_bf16_f32 v97, v102, v103
	v_cvt_pk_bf16_f32 v98, v104, v105
	v_cvt_pk_bf16_f32 v99, v106, v107
	v_max_f32_e32 v88, 0, v88
	v_max_f32_e32 v89, 0, v89
	global_store_dwordx4 v[108:109], v[96:99], off offset:256
	s_nop 1
	v_or_b32_e32 v96, 32, v154
	v_pk_mul_f32 v[98:99], v[88:89], v[88:89]
	v_max_f32_e32 v89, v90, v90
	v_ashrrev_i32_e32 v97, 31, v96
	v_max_f32_e32 v88, v94, v94
	v_max_f32_e32 v90, 0, v89
	v_max_f32_e32 v89, v95, v95
	v_lshlrev_b64 v[96:97], 13, v[96:97]
	v_max_f32_e32 v92, 0, v92
	v_max_f32_e32 v93, 0, v93
	v_max_f32_e32 v88, 0, v88
	v_max_f32_e32 v89, 0, v89
	v_max_f32_e32 v91, 0, v91
	v_lshl_add_u64 v[96:97], s[46:47], 0, v[96:97]
	v_pk_mul_f32 v[92:93], v[92:93], v[92:93]
	v_pk_mul_f32 v[94:95], v[88:89], v[88:89]
	v_pk_mul_f32 v[100:101], v[90:91], v[90:91]
	v_cvt_pk_bf16_f32 v88, v92, v93
	v_cvt_pk_bf16_f32 v89, v94, v95
	v_cvt_pk_bf16_f32 v90, v98, v99
	v_cvt_pk_bf16_f32 v91, v100, v101
	v_lshl_add_u64 v[92:93], v[96:97], 0, v[126:127]
	v_max_f32_e32 v80, 0, v80
	v_max_f32_e32 v81, 0, v81
	global_store_dwordx4 v[92:93], v[88:91], off
	s_nop 1
	v_pk_mul_f32 v[88:89], v[80:81], v[80:81]
	v_max_f32_e32 v81, v82, v82
	v_max_f32_e32 v80, v86, v86
	v_max_f32_e32 v82, 0, v81
	v_max_f32_e32 v81, v87, v87
	v_max_f32_e32 v84, 0, v84
	v_max_f32_e32 v85, 0, v85
	v_max_f32_e32 v80, 0, v80
	v_max_f32_e32 v81, 0, v81
	v_max_f32_e32 v83, 0, v83
	v_pk_mul_f32 v[84:85], v[84:85], v[84:85]
	v_pk_mul_f32 v[86:87], v[80:81], v[80:81]
	v_pk_mul_f32 v[90:91], v[82:83], v[82:83]
	v_cvt_pk_bf16_f32 v80, v84, v85
	v_cvt_pk_bf16_f32 v81, v86, v87
	v_cvt_pk_bf16_f32 v82, v88, v89
	v_cvt_pk_bf16_f32 v83, v90, v91
	v_max_f32_e32 v72, 0, v72
	v_max_f32_e32 v73, 0, v73
	global_store_dwordx4 v[92:93], v[80:83], off offset:256
	s_nop 1
	v_or_b32_e32 v80, 48, v154
	v_pk_mul_f32 v[82:83], v[72:73], v[72:73]
	v_max_f32_e32 v73, v74, v74
	v_ashrrev_i32_e32 v81, 31, v80
	v_max_f32_e32 v72, v78, v78
	v_max_f32_e32 v74, 0, v73
	v_max_f32_e32 v73, v79, v79
	v_lshlrev_b64 v[80:81], 13, v[80:81]
	v_max_f32_e32 v76, 0, v76
	v_max_f32_e32 v77, 0, v77
	v_max_f32_e32 v72, 0, v72
	v_max_f32_e32 v73, 0, v73
	v_max_f32_e32 v75, 0, v75
	v_lshl_add_u64 v[80:81], s[46:47], 0, v[80:81]
	v_pk_mul_f32 v[76:77], v[76:77], v[76:77]
	v_pk_mul_f32 v[78:79], v[72:73], v[72:73]
	v_pk_mul_f32 v[84:85], v[74:75], v[74:75]
	v_cvt_pk_bf16_f32 v72, v76, v77
	v_cvt_pk_bf16_f32 v73, v78, v79
	v_cvt_pk_bf16_f32 v74, v82, v83
	v_cvt_pk_bf16_f32 v75, v84, v85
	v_lshl_add_u64 v[76:77], v[80:81], 0, v[126:127]
	v_max_f32_e32 v64, 0, v64
	v_max_f32_e32 v65, 0, v65
	global_store_dwordx4 v[76:77], v[72:75], off
	s_nop 1
	v_pk_mul_f32 v[72:73], v[64:65], v[64:65]
	v_max_f32_e32 v65, v66, v66
	v_max_f32_e32 v64, v70, v70
	v_max_f32_e32 v66, 0, v65
	v_max_f32_e32 v65, v71, v71
	v_max_f32_e32 v68, 0, v68
	v_max_f32_e32 v69, 0, v69
	v_max_f32_e32 v64, 0, v64
	v_max_f32_e32 v65, 0, v65
	v_max_f32_e32 v67, 0, v67
	v_pk_mul_f32 v[68:69], v[68:69], v[68:69]
	v_pk_mul_f32 v[70:71], v[64:65], v[64:65]
	v_pk_mul_f32 v[74:75], v[66:67], v[66:67]
	v_cvt_pk_bf16_f32 v64, v68, v69
	v_cvt_pk_bf16_f32 v65, v70, v71
	v_cvt_pk_bf16_f32 v66, v72, v73
	v_cvt_pk_bf16_f32 v67, v74, v75
	v_max_f32_e32 v56, 0, v56
	v_max_f32_e32 v57, 0, v57
	global_store_dwordx4 v[76:77], v[64:67], off offset:256
	s_nop 1
	v_pk_mul_f32 v[64:65], v[56:57], v[56:57]
	v_max_f32_e32 v57, v58, v58
	v_max_f32_e32 v56, v62, v62
	v_max_f32_e32 v58, 0, v57
	v_max_f32_e32 v57, v63, v63
	v_max_f32_e32 v56, 0, v56
	v_max_f32_e32 v57, 0, v57
	v_max_f32_e32 v60, 0, v60
	v_max_f32_e32 v61, 0, v61
	v_max_f32_e32 v59, 0, v59
	v_pk_mul_f32 v[62:63], v[56:57], v[56:57]
	v_pk_mul_f32 v[60:61], v[60:61], v[60:61]
	v_pk_mul_f32 v[66:67], v[58:59], v[58:59]
	v_cvt_pk_bf16_f32 v57, v62, v63
	v_add_co_u32_e32 v62, vcc, s70, v120
	v_cvt_pk_bf16_f32 v56, v60, v61
	v_cvt_pk_bf16_f32 v58, v64, v65
	v_cvt_pk_bf16_f32 v59, v66, v67
	v_addc_co_u32_e32 v63, vcc, 0, v121, vcc
	v_max_f32_e32 v48, 0, v48
	v_max_f32_e32 v49, 0, v49
	global_store_dwordx4 v[62:63], v[56:59], off
	s_nop 1
	v_pk_mul_f32 v[56:57], v[48:49], v[48:49]
	v_max_f32_e32 v49, v50, v50
	v_max_f32_e32 v48, v54, v54
	v_max_f32_e32 v50, 0, v49
	v_max_f32_e32 v49, v55, v55
	v_max_f32_e32 v52, 0, v52
	v_max_f32_e32 v53, 0, v53
	v_max_f32_e32 v48, 0, v48
	v_max_f32_e32 v49, 0, v49
	v_max_f32_e32 v51, 0, v51
	v_pk_mul_f32 v[52:53], v[52:53], v[52:53]
	v_pk_mul_f32 v[54:55], v[48:49], v[48:49]
	v_pk_mul_f32 v[58:59], v[50:51], v[50:51]
	v_lshl_add_u64 v[60:61], v[120:121], 0, s[10:11]
	v_cvt_pk_bf16_f32 v48, v52, v53
	v_cvt_pk_bf16_f32 v49, v54, v55
	v_cvt_pk_bf16_f32 v50, v56, v57
	v_cvt_pk_bf16_f32 v51, v58, v59
	v_max_f32_e32 v40, 0, v40
	v_max_f32_e32 v41, 0, v41
	global_store_dwordx4 v[60:61], v[48:51], off offset:256
	s_nop 1
	v_pk_mul_f32 v[48:49], v[40:41], v[40:41]
	v_max_f32_e32 v41, v42, v42
	v_max_f32_e32 v40, v46, v46
	v_max_f32_e32 v42, 0, v41
	v_max_f32_e32 v41, v47, v47
	v_max_f32_e32 v40, 0, v40
	v_max_f32_e32 v41, 0, v41
	v_max_f32_e32 v44, 0, v44
	v_max_f32_e32 v45, 0, v45
	v_max_f32_e32 v43, 0, v43
	v_pk_mul_f32 v[46:47], v[40:41], v[40:41]
	v_pk_mul_f32 v[44:45], v[44:45], v[44:45]
	v_pk_mul_f32 v[50:51], v[42:43], v[42:43]
	v_cvt_pk_bf16_f32 v41, v46, v47
	v_add_co_u32_e32 v46, vcc, s71, v120
	v_cvt_pk_bf16_f32 v40, v44, v45
	v_cvt_pk_bf16_f32 v42, v48, v49
	v_cvt_pk_bf16_f32 v43, v50, v51
	v_addc_co_u32_e32 v47, vcc, 0, v121, vcc
	v_max_f32_e32 v32, 0, v32
	v_max_f32_e32 v33, 0, v33
	global_store_dwordx4 v[46:47], v[40:43], off
	s_nop 1
	v_pk_mul_f32 v[40:41], v[32:33], v[32:33]
	v_max_f32_e32 v33, v34, v34
	v_max_f32_e32 v32, v38, v38
	v_max_f32_e32 v34, 0, v33
	v_max_f32_e32 v33, v39, v39
	v_max_f32_e32 v36, 0, v36
	v_max_f32_e32 v37, 0, v37
	v_max_f32_e32 v32, 0, v32
	v_max_f32_e32 v33, 0, v33
	v_max_f32_e32 v35, 0, v35
	v_pk_mul_f32 v[36:37], v[36:37], v[36:37]
	v_pk_mul_f32 v[38:39], v[32:33], v[32:33]
	v_pk_mul_f32 v[42:43], v[34:35], v[34:35]
	v_lshl_add_u64 v[44:45], v[120:121], 0, s[12:13]
	v_cvt_pk_bf16_f32 v32, v36, v37
	v_cvt_pk_bf16_f32 v33, v38, v39
	v_cvt_pk_bf16_f32 v34, v40, v41
	v_cvt_pk_bf16_f32 v35, v42, v43
	v_max_f32_e32 v24, 0, v24
	v_max_f32_e32 v25, 0, v25
	global_store_dwordx4 v[44:45], v[32:35], off offset:256
	s_nop 1
	v_pk_mul_f32 v[32:33], v[24:25], v[24:25]
	v_max_f32_e32 v25, v26, v26
	v_max_f32_e32 v24, v30, v30
	v_max_f32_e32 v26, 0, v25
	v_max_f32_e32 v25, v31, v31
	v_max_f32_e32 v24, 0, v24
	v_max_f32_e32 v25, 0, v25
	v_max_f32_e32 v28, 0, v28
	v_max_f32_e32 v29, 0, v29
	v_max_f32_e32 v27, 0, v27
	v_pk_mul_f32 v[30:31], v[24:25], v[24:25]
	v_pk_mul_f32 v[28:29], v[28:29], v[28:29]
	v_pk_mul_f32 v[34:35], v[26:27], v[26:27]
	v_cvt_pk_bf16_f32 v25, v30, v31
	v_add_co_u32_e32 v30, vcc, s72, v120
	v_cvt_pk_bf16_f32 v24, v28, v29
	v_cvt_pk_bf16_f32 v26, v32, v33
	v_cvt_pk_bf16_f32 v27, v34, v35
	v_addc_co_u32_e32 v31, vcc, 0, v121, vcc
	v_max_f32_e32 v16, 0, v16
	v_max_f32_e32 v17, 0, v17
	global_store_dwordx4 v[30:31], v[24:27], off
	s_nop 1
	v_pk_mul_f32 v[24:25], v[16:17], v[16:17]
	v_max_f32_e32 v17, v18, v18
	v_max_f32_e32 v16, v22, v22
	v_max_f32_e32 v18, 0, v17
	v_max_f32_e32 v17, v23, v23
	v_max_f32_e32 v20, 0, v20
	v_max_f32_e32 v21, 0, v21
	v_max_f32_e32 v16, 0, v16
	v_max_f32_e32 v17, 0, v17
	v_max_f32_e32 v19, 0, v19
	v_pk_mul_f32 v[20:21], v[20:21], v[20:21]
	v_pk_mul_f32 v[22:23], v[16:17], v[16:17]
	v_pk_mul_f32 v[26:27], v[18:19], v[18:19]
	v_lshl_add_u64 v[28:29], v[120:121], 0, s[14:15]
	v_cvt_pk_bf16_f32 v16, v20, v21
	v_cvt_pk_bf16_f32 v17, v22, v23
	v_cvt_pk_bf16_f32 v18, v24, v25
	v_cvt_pk_bf16_f32 v19, v26, v27
	v_max_f32_e32 v8, 0, v8
	v_max_f32_e32 v9, 0, v9
	global_store_dwordx4 v[28:29], v[16:19], off offset:256
	s_nop 1
	v_pk_mul_f32 v[16:17], v[8:9], v[8:9]
	v_max_f32_e32 v9, v10, v10
	v_max_f32_e32 v8, v14, v14
	v_max_f32_e32 v10, 0, v9
	v_max_f32_e32 v9, v15, v15
	v_max_f32_e32 v8, 0, v8
	v_max_f32_e32 v9, 0, v9
	v_max_f32_e32 v12, 0, v12
	v_max_f32_e32 v13, 0, v13
	v_max_f32_e32 v11, 0, v11
	v_pk_mul_f32 v[14:15], v[8:9], v[8:9]
	v_pk_mul_f32 v[12:13], v[12:13], v[12:13]
	v_pk_mul_f32 v[18:19], v[10:11], v[10:11]
	v_cvt_pk_bf16_f32 v9, v14, v15
	v_add_co_u32_e32 v14, vcc, s73, v120
	v_cvt_pk_bf16_f32 v8, v12, v13
	v_cvt_pk_bf16_f32 v10, v16, v17
	v_cvt_pk_bf16_f32 v11, v18, v19
	v_addc_co_u32_e32 v15, vcc, 0, v121, vcc
	v_max_f32_e32 v0, 0, v0
	v_max_f32_e32 v1, 0, v1
	global_store_dwordx4 v[14:15], v[8:11], off
	s_nop 1
	v_pk_mul_f32 v[8:9], v[0:1], v[0:1]
	v_max_f32_e32 v1, v2, v2
	v_max_f32_e32 v0, v6, v6
	v_max_f32_e32 v2, 0, v1
	v_max_f32_e32 v1, v7, v7
	v_max_f32_e32 v4, 0, v4
	v_max_f32_e32 v5, 0, v5
	v_max_f32_e32 v0, 0, v0
	v_max_f32_e32 v1, 0, v1
	v_max_f32_e32 v3, 0, v3
	v_pk_mul_f32 v[4:5], v[4:5], v[4:5]
	v_pk_mul_f32 v[6:7], v[0:1], v[0:1]
	v_pk_mul_f32 v[10:11], v[2:3], v[2:3]
	v_lshl_add_u64 v[12:13], v[120:121], 0, s[16:17]
	v_cvt_pk_bf16_f32 v0, v4, v5
	v_cvt_pk_bf16_f32 v1, v6, v7
	v_cvt_pk_bf16_f32 v2, v8, v9
	v_cvt_pk_bf16_f32 v3, v10, v11
	s_and_b64 vcc, exec, s[4:5]
	s_mov_b32 s74, s18
	s_mov_b32 s30, s20
	s_mov_b64 s[36:37], s[28:29]
	s_mov_b64 s[34:35], s[26:27]
	global_store_dwordx4 v[12:13], v[0:3], off offset:256
	s_cbranch_vccz .LBB0_1284
	s_waitcnt vmcnt(16)
	s_cmpk_gt_u32 s40, 0xff
	s_cbranch_scc1 .LBB0_1295
	s_barrier

.LBB0_1310:
	ds_read_b128 v[154:157], v151
	ds_read_b128 v[158:161], v151 offset:1024
	ds_read_b128 v[162:165], v151 offset:2048
	ds_read_b128 v[166:169], v151 offset:3072
	s_add_u32 s38, s36, 0xfffc0080
	s_addc_u32 s39, s37, -1
	s_cmp_eq_u32 s77, 12
	s_cselect_b32 s41, s27, s39
	s_cselect_b32 s40, s73, s38
	s_cselect_b32 s39, s21, s76
	s_cselect_b32 s38, s74, s75
	v_lshl_add_u64 v[202:203], s[36:37], 0, v[138:139]
	s_add_i32 m0, s35, 0xc000
	ds_read_b128 v[170:173], v152
	ds_read_b128 v[174:177], v152 offset:1024
	ds_read_b128 v[178:181], v152 offset:2048
	ds_read_b128 v[182:185], v152 offset:3072
	ds_read_b128 v[186:189], v152 offset:4096
	ds_read_b128 v[190:193], v152 offset:5120
	ds_read_b128 v[194:197], v152 offset:6144
	ds_read_b128 v[198:201], v152 offset:7168
	global_load_lds_dwordx4 v[202:203], off
	v_lshl_add_u64 v[202:203], s[36:37], 0, v[140:141]
	s_add_i32 m0, s35, 0xe000
	s_nop 0
	global_load_lds_dwordx4 v[202:203], off
	s_waitcnt lgkmcnt(8)
	s_barrier
	s_waitcnt lgkmcnt(0)
	s_waitcnt lgkmcnt(0)
	v_mfma_f32_16x16x32_bf16 v[124:127], v[154:157], v[170:173], v[124:127]
	v_mfma_f32_16x16x32_bf16 v[120:123], v[162:165], v[170:173], v[120:123]
	v_mfma_f32_16x16x32_bf16 v[108:111], v[154:157], v[178:181], v[108:111]
	v_mfma_f32_16x16x32_bf16 v[104:107], v[162:165], v[178:181], v[104:107]
	v_mfma_f32_16x16x32_bf16 v[92:95], v[154:157], v[186:189], v[92:95]
	v_mfma_f32_16x16x32_bf16 v[88:91], v[162:165], v[186:189], v[88:91]
	v_mfma_f32_16x16x32_bf16 v[76:79], v[154:157], v[194:197], v[76:79]
	v_mfma_f32_16x16x32_bf16 v[72:75], v[162:165], v[194:197], v[72:75]
	v_mfma_f32_16x16x32_bf16 v[124:127], v[158:161], v[174:177], v[124:127]
	v_mfma_f32_16x16x32_bf16 v[120:123], v[166:169], v[174:177], v[120:123]
	v_mfma_f32_16x16x32_bf16 v[108:111], v[158:161], v[182:185], v[108:111]
	v_mfma_f32_16x16x32_bf16 v[104:107], v[166:169], v[182:185], v[104:107]
	v_mfma_f32_16x16x32_bf16 v[92:95], v[158:161], v[190:193], v[92:95]
	v_mfma_f32_16x16x32_bf16 v[88:91], v[166:169], v[190:193], v[88:91]
	v_mfma_f32_16x16x32_bf16 v[76:79], v[158:161], v[198:201], v[76:79]
	v_mfma_f32_16x16x32_bf16 v[72:75], v[166:169], v[198:201], v[72:75]
	s_barrier
	s_add_i32 s78, s62, s52
	v_lshl_add_u64 v[218:219], s[38:39], 0, v[132:133]
	s_mov_b32 m0, s78
	ds_read_b128 v[202:205], v153
	ds_read_b128 v[206:209], v153 offset:1024
	ds_read_b128 v[210:213], v153 offset:2048
	ds_read_b128 v[214:217], v153 offset:3072
	global_load_lds_dwordx4 v[218:219], off
	v_lshl_add_u64 v[220:221], s[38:39], 0, v[136:137]
	s_add_i32 m0, s78, 0x2000
	s_nop 0
	global_load_lds_dwordx4 v[220:221], off
	s_barrier
	s_waitcnt lgkmcnt(0)
	s_waitcnt lgkmcnt(0)
	v_mfma_f32_16x16x32_bf16 v[116:119], v[202:205], v[170:173], v[116:119]
	v_mfma_f32_16x16x32_bf16 v[112:115], v[210:213], v[170:173], v[112:115]
	v_mfma_f32_16x16x32_bf16 v[100:103], v[202:205], v[178:181], v[100:103]
	v_mfma_f32_16x16x32_bf16 v[96:99], v[210:213], v[178:181], v[96:99]
	v_mfma_f32_16x16x32_bf16 v[84:87], v[202:205], v[186:189], v[84:87]
	v_mfma_f32_16x16x32_bf16 v[80:83], v[210:213], v[186:189], v[80:83]
	v_mfma_f32_16x16x32_bf16 v[68:71], v[202:205], v[194:197], v[68:71]
	v_mfma_f32_16x16x32_bf16 v[64:67], v[210:213], v[194:197], v[64:67]
	v_mfma_f32_16x16x32_bf16 v[116:119], v[206:209], v[174:177], v[116:119]
	v_mfma_f32_16x16x32_bf16 v[112:115], v[214:217], v[174:177], v[112:115]
	v_mfma_f32_16x16x32_bf16 v[100:103], v[206:209], v[182:185], v[100:103]
	v_mfma_f32_16x16x32_bf16 v[96:99], v[214:217], v[182:185], v[96:99]
	v_mfma_f32_16x16x32_bf16 v[84:87], v[206:209], v[190:193], v[84:87]
	v_mfma_f32_16x16x32_bf16 v[80:83], v[214:217], v[190:193], v[80:83]
	v_mfma_f32_16x16x32_bf16 v[68:71], v[206:209], v[198:201], v[68:71]
	v_mfma_f32_16x16x32_bf16 v[64:67], v[214:217], v[198:201], v[64:67]
	s_mov_b32 m0, s35
	v_lshl_add_u64 v[222:223], s[40:41], 0, v[130:131]
	s_barrier
	ds_read_b128 v[170:173], v152 offset:16384
	ds_read_b128 v[174:177], v152 offset:17408
	ds_read_b128 v[178:181], v152 offset:18432
	ds_read_b128 v[182:185], v152 offset:19456
	ds_read_b128 v[186:189], v152 offset:20480
	ds_read_b128 v[190:193], v152 offset:21504
	ds_read_b128 v[194:197], v152 offset:22528
	ds_read_b128 v[198:201], v152 offset:23552
	global_load_lds_dwordx4 v[222:223], off
	v_lshl_add_u64 v[224:225], s[40:41], 0, v[134:135]
	s_mov_b32 m0, s53
	s_nop 0
	global_load_lds_dwordx4 v[224:225], off
	s_barrier
	s_waitcnt lgkmcnt(0)
	s_waitcnt lgkmcnt(0)
	v_mfma_f32_16x16x32_bf16 v[60:63], v[154:157], v[170:173], v[60:63]
	v_mfma_f32_16x16x32_bf16 v[56:59], v[162:165], v[170:173], v[56:59]
	v_mfma_f32_16x16x32_bf16 v[44:47], v[154:157], v[178:181], v[44:47]
	v_mfma_f32_16x16x32_bf16 v[40:43], v[162:165], v[178:181], v[40:43]
	v_mfma_f32_16x16x32_bf16 v[28:31], v[154:157], v[186:189], v[28:31]
	v_mfma_f32_16x16x32_bf16 v[24:27], v[162:165], v[186:189], v[24:27]
	v_mfma_f32_16x16x32_bf16 v[12:15], v[154:157], v[194:197], v[12:15]
	v_mfma_f32_16x16x32_bf16 v[8:11], v[162:165], v[194:197], v[8:11]
	v_mfma_f32_16x16x32_bf16 v[60:63], v[158:161], v[174:177], v[60:63]
	v_mfma_f32_16x16x32_bf16 v[56:59], v[166:169], v[174:177], v[56:59]
	v_mfma_f32_16x16x32_bf16 v[44:47], v[158:161], v[182:185], v[44:47]
	v_mfma_f32_16x16x32_bf16 v[40:43], v[166:169], v[182:185], v[40:43]
	v_mfma_f32_16x16x32_bf16 v[28:31], v[158:161], v[190:193], v[28:31]
	v_mfma_f32_16x16x32_bf16 v[24:27], v[166:169], v[190:193], v[24:27]
	v_mfma_f32_16x16x32_bf16 v[12:15], v[158:161], v[198:201], v[12:15]
	v_mfma_f32_16x16x32_bf16 v[8:11], v[166:169], v[198:201], v[8:11]
	s_barrier
	s_add_u32 s78, s38, 0x40000
	s_addc_u32 s79, s39, 0
	s_add_i32 s80, s63, s52
	v_lshl_add_u64 v[154:155], s[78:79], 0, v[132:133]
	s_mov_b32 m0, s80
	s_nop 0
	global_load_lds_dwordx4 v[154:155], off
	v_lshl_add_u64 v[154:155], s[78:79], 0, v[136:137]
	s_add_i32 m0, s80, 0x2000
	s_nop 0
	global_load_lds_dwordx4 v[154:155], off
	s_waitcnt vmcnt(6)
	s_barrier
	v_mfma_f32_16x16x32_bf16 v[52:55], v[202:205], v[170:173], v[52:55]
	v_mfma_f32_16x16x32_bf16 v[48:51], v[210:213], v[170:173], v[48:51]
	v_mfma_f32_16x16x32_bf16 v[36:39], v[202:205], v[178:181], v[36:39]
	v_mfma_f32_16x16x32_bf16 v[32:35], v[210:213], v[178:181], v[32:35]
	v_mfma_f32_16x16x32_bf16 v[20:23], v[202:205], v[186:189], v[20:23]
	v_mfma_f32_16x16x32_bf16 v[16:19], v[210:213], v[186:189], v[16:19]
	v_mfma_f32_16x16x32_bf16 v[4:7], v[202:205], v[194:197], v[4:7]
	v_mfma_f32_16x16x32_bf16 v[0:3], v[210:213], v[194:197], v[0:3]
	v_mfma_f32_16x16x32_bf16 v[52:55], v[206:209], v[174:177], v[52:55]
	v_mfma_f32_16x16x32_bf16 v[48:51], v[214:217], v[174:177], v[48:51]
	v_mfma_f32_16x16x32_bf16 v[36:39], v[206:209], v[182:185], v[36:39]
	v_mfma_f32_16x16x32_bf16 v[32:35], v[214:217], v[182:185], v[32:35]
	v_mfma_f32_16x16x32_bf16 v[20:23], v[206:209], v[190:193], v[20:23]
	v_mfma_f32_16x16x32_bf16 v[16:19], v[214:217], v[190:193], v[16:19]
	v_mfma_f32_16x16x32_bf16 v[4:7], v[206:209], v[198:201], v[4:7]
	v_mfma_f32_16x16x32_bf16 v[0:3], v[214:217], v[198:201], v[0:3]
	s_add_i32 s78, 0, 0x18000
	v_add_u32_e32 v166, s78, v149
	s_barrier
	ds_read_b128 v[154:157], v166
	ds_read_b128 v[158:161], v166 offset:1024
	ds_read_b128 v[162:165], v166 offset:2048
	ds_read_b128 v[166:169], v166 offset:3072
	s_add_u32 s40, s40, 0x40000
	s_addc_u32 s41, s41, 0
	s_mov_b32 m0, s54
	v_lshl_add_u64 v[202:203], s[40:41], 0, v[130:131]
	ds_read_b128 v[170:173], v152 offset:32768
	ds_read_b128 v[174:177], v152 offset:33792
	ds_read_b128 v[178:181], v152 offset:34816
	ds_read_b128 v[182:185], v152 offset:35840
	ds_read_b128 v[186:189], v152 offset:36864
	ds_read_b128 v[190:193], v152 offset:37888
	ds_read_b128 v[194:197], v152 offset:38912
	ds_read_b128 v[198:201], v152 offset:39936
	global_load_lds_dwordx4 v[202:203], off
	v_lshl_add_u64 v[202:203], s[40:41], 0, v[134:135]
	s_mov_b32 m0, s55
	s_nop 0
	global_load_lds_dwordx4 v[202:203], off
	s_waitcnt lgkmcnt(8)
	s_barrier
	s_waitcnt lgkmcnt(0)
	s_waitcnt lgkmcnt(0)
	v_mfma_f32_16x16x32_bf16 v[124:127], v[154:157], v[170:173], v[124:127]
	v_mfma_f32_16x16x32_bf16 v[120:123], v[162:165], v[170:173], v[120:123]
	v_mfma_f32_16x16x32_bf16 v[108:111], v[154:157], v[178:181], v[108:111]
	v_mfma_f32_16x16x32_bf16 v[104:107], v[162:165], v[178:181], v[104:107]
	v_mfma_f32_16x16x32_bf16 v[92:95], v[154:157], v[186:189], v[92:95]
	v_mfma_f32_16x16x32_bf16 v[88:91], v[162:165], v[186:189], v[88:91]
	v_mfma_f32_16x16x32_bf16 v[76:79], v[154:157], v[194:197], v[76:79]
	v_mfma_f32_16x16x32_bf16 v[72:75], v[162:165], v[194:197], v[72:75]
	v_mfma_f32_16x16x32_bf16 v[124:127], v[158:161], v[174:177], v[124:127]
	v_mfma_f32_16x16x32_bf16 v[120:123], v[166:169], v[174:177], v[120:123]
	v_mfma_f32_16x16x32_bf16 v[108:111], v[158:161], v[182:185], v[108:111]
	v_mfma_f32_16x16x32_bf16 v[104:107], v[166:169], v[182:185], v[104:107]
	v_mfma_f32_16x16x32_bf16 v[92:95], v[158:161], v[190:193], v[92:95]
	v_mfma_f32_16x16x32_bf16 v[88:91], v[166:169], v[190:193], v[88:91]
	v_mfma_f32_16x16x32_bf16 v[76:79], v[158:161], v[198:201], v[76:79]
	v_mfma_f32_16x16x32_bf16 v[72:75], v[166:169], v[198:201], v[72:75]
	s_barrier
	s_add_i32 s40, 0, 0x1c000
	s_add_i32 s41, s78, s52
	v_add_u32_e32 v214, s40, v149
	v_lshl_add_u64 v[218:219], v[218:219], 0, s[10:11]
	s_mov_b32 m0, s41
	ds_read_b128 v[202:205], v214
	ds_read_b128 v[206:209], v214 offset:1024
	ds_read_b128 v[210:213], v214 offset:2048
	ds_read_b128 v[214:217], v214 offset:3072
	global_load_lds_dwordx4 v[218:219], off
	v_lshl_add_u64 v[218:219], v[220:221], 0, s[10:11]
	s_add_i32 m0, s41, 0x2000
	s_nop 0
	global_load_lds_dwordx4 v[218:219], off
	s_barrier
	s_waitcnt lgkmcnt(0)
	s_waitcnt lgkmcnt(0)
	v_mfma_f32_16x16x32_bf16 v[116:119], v[202:205], v[170:173], v[116:119]
	v_mfma_f32_16x16x32_bf16 v[112:115], v[210:213], v[170:173], v[112:115]
	v_mfma_f32_16x16x32_bf16 v[100:103], v[202:205], v[178:181], v[100:103]
	v_mfma_f32_16x16x32_bf16 v[96:99], v[210:213], v[178:181], v[96:99]
	v_mfma_f32_16x16x32_bf16 v[84:87], v[202:205], v[186:189], v[84:87]
	v_mfma_f32_16x16x32_bf16 v[80:83], v[210:213], v[186:189], v[80:83]
	v_mfma_f32_16x16x32_bf16 v[68:71], v[202:205], v[194:197], v[68:71]
	v_mfma_f32_16x16x32_bf16 v[64:67], v[210:213], v[194:197], v[64:67]
	v_mfma_f32_16x16x32_bf16 v[116:119], v[206:209], v[174:177], v[116:119]
	v_mfma_f32_16x16x32_bf16 v[112:115], v[214:217], v[174:177], v[112:115]
	v_mfma_f32_16x16x32_bf16 v[100:103], v[206:209], v[182:185], v[100:103]
	v_mfma_f32_16x16x32_bf16 v[96:99], v[214:217], v[182:185], v[96:99]
	v_mfma_f32_16x16x32_bf16 v[84:87], v[206:209], v[190:193], v[84:87]
	v_mfma_f32_16x16x32_bf16 v[80:83], v[214:217], v[190:193], v[80:83]
	v_mfma_f32_16x16x32_bf16 v[68:71], v[206:209], v[198:201], v[68:71]
	v_mfma_f32_16x16x32_bf16 v[64:67], v[214:217], v[198:201], v[64:67]
	s_mov_b32 m0, s57
	v_lshl_add_u64 v[218:219], v[222:223], 0, s[10:11]
	s_barrier
	ds_read_b128 v[170:173], v152 offset:49152
	ds_read_b128 v[174:177], v152 offset:50176
	ds_read_b128 v[178:181], v152 offset:51200
	ds_read_b128 v[182:185], v152 offset:52224
	ds_read_b128 v[186:189], v152 offset:53248
	ds_read_b128 v[190:193], v152 offset:54272
	ds_read_b128 v[194:197], v152 offset:55296
	ds_read_b128 v[198:201], v152 offset:56320
	global_load_lds_dwordx4 v[218:219], off
	v_lshl_add_u64 v[218:219], v[224:225], 0, s[10:11]
	s_mov_b32 m0, s60
	s_nop 0
	global_load_lds_dwordx4 v[218:219], off
	s_barrier
	s_waitcnt lgkmcnt(0)
	s_waitcnt lgkmcnt(0)
	v_mfma_f32_16x16x32_bf16 v[60:63], v[154:157], v[170:173], v[60:63]
	v_mfma_f32_16x16x32_bf16 v[56:59], v[162:165], v[170:173], v[56:59]
	v_mfma_f32_16x16x32_bf16 v[44:47], v[154:157], v[178:181], v[44:47]
	v_mfma_f32_16x16x32_bf16 v[40:43], v[162:165], v[178:181], v[40:43]
	v_mfma_f32_16x16x32_bf16 v[28:31], v[154:157], v[186:189], v[28:31]
	v_mfma_f32_16x16x32_bf16 v[24:27], v[162:165], v[186:189], v[24:27]
	v_mfma_f32_16x16x32_bf16 v[12:15], v[154:157], v[194:197], v[12:15]
	v_mfma_f32_16x16x32_bf16 v[8:11], v[162:165], v[194:197], v[8:11]
	v_mfma_f32_16x16x32_bf16 v[60:63], v[158:161], v[174:177], v[60:63]
	v_mfma_f32_16x16x32_bf16 v[56:59], v[166:169], v[174:177], v[56:59]
	v_mfma_f32_16x16x32_bf16 v[44:47], v[158:161], v[182:185], v[44:47]
	v_mfma_f32_16x16x32_bf16 v[40:43], v[166:169], v[182:185], v[40:43]
	v_mfma_f32_16x16x32_bf16 v[28:31], v[158:161], v[190:193], v[28:31]
	v_mfma_f32_16x16x32_bf16 v[24:27], v[166:169], v[190:193], v[24:27]
	v_mfma_f32_16x16x32_bf16 v[12:15], v[158:161], v[198:201], v[12:15]
	v_mfma_f32_16x16x32_bf16 v[8:11], v[166:169], v[198:201], v[8:11]
	s_barrier
	s_add_u32 s38, s38, 0x40080
	s_addc_u32 s39, s39, 0
	s_add_i32 s40, s40, s52
	v_lshl_add_u64 v[154:155], s[38:39], 0, v[132:133]
	s_mov_b32 m0, s40
	s_nop 0
	global_load_lds_dwordx4 v[154:155], off
	v_lshl_add_u64 v[154:155], s[38:39], 0, v[136:137]
	s_add_i32 m0, s40, 0x2000
	s_nop 0
	global_load_lds_dwordx4 v[154:155], off
	s_waitcnt vmcnt(6)
	s_barrier
	v_mfma_f32_16x16x32_bf16 v[52:55], v[202:205], v[170:173], v[52:55]
	v_mfma_f32_16x16x32_bf16 v[48:51], v[210:213], v[170:173], v[48:51]
	v_mfma_f32_16x16x32_bf16 v[36:39], v[202:205], v[178:181], v[36:39]
	v_mfma_f32_16x16x32_bf16 v[32:35], v[210:213], v[178:181], v[32:35]
	v_mfma_f32_16x16x32_bf16 v[20:23], v[202:205], v[186:189], v[20:23]
	v_mfma_f32_16x16x32_bf16 v[16:19], v[210:213], v[186:189], v[16:19]
	v_mfma_f32_16x16x32_bf16 v[4:7], v[202:205], v[194:197], v[4:7]
	v_mfma_f32_16x16x32_bf16 v[0:3], v[210:213], v[194:197], v[0:3]
	v_mfma_f32_16x16x32_bf16 v[52:55], v[206:209], v[174:177], v[52:55]
	v_mfma_f32_16x16x32_bf16 v[48:51], v[214:217], v[174:177], v[48:51]
	v_mfma_f32_16x16x32_bf16 v[36:39], v[206:209], v[182:185], v[36:39]
	v_mfma_f32_16x16x32_bf16 v[32:35], v[214:217], v[182:185], v[32:35]
	v_mfma_f32_16x16x32_bf16 v[20:23], v[206:209], v[190:193], v[20:23]
	v_mfma_f32_16x16x32_bf16 v[16:19], v[214:217], v[190:193], v[16:19]
	v_mfma_f32_16x16x32_bf16 v[4:7], v[206:209], v[198:201], v[4:7]
	v_mfma_f32_16x16x32_bf16 v[0:3], v[214:217], v[198:201], v[0:3]
	s_add_i32 s77, s77, 2
	s_add_u32 s36, s36, 0x100
	s_addc_u32 s37, s37, 0
	s_add_u32 s75, s75, 0x100
	s_addc_u32 s76, s76, 0
	s_cmp_gt_u32 s77, 13
	s_barrier
	s_cbranch_scc0 .LBB0_1310
	v_lshl_add_u32 v154, s34, 8, v148
	v_lshl_or_b32 v156, s72, 8, v150
	v_ashrrev_i32_e32 v155, 31, v154
	v_max_f32_e32 v126, 0, v126
	v_max_f32_e32 v127, 0, v127
	v_lshlrev_b64 v[158:159], 13, v[154:155]
	v_max_f32_e32 v124, 0, v124
	v_max_f32_e32 v120, 0, v120
	v_max_f32_e32 v125, 0, v125
	v_max_f32_e32 v121, 0, v121
	v_max_f32_e32 v122, 0, v122
	v_max_f32_e32 v123, 0, v123
	v_pk_mul_f32 v[126:127], v[126:127], v[126:127]
	v_ashrrev_i32_e32 v157, 31, v156
	v_lshl_add_u64 v[158:159], s[46:47], 0, v[158:159]
	v_pk_mul_f32 v[124:125], v[124:125], v[124:125]
	v_pk_mul_f32 v[120:121], v[120:121], v[120:121]
	v_pk_mul_f32 v[160:161], v[122:123], v[122:123]
	v_cvt_pk_bf16_f32 v123, v126, v127
	v_lshlrev_b64 v[126:127], 1, v[156:157]
	v_cvt_pk_bf16_f32 v122, v124, v125
	v_cvt_pk_bf16_f32 v124, v120, v121
	v_cvt_pk_bf16_f32 v125, v160, v161
	v_lshl_add_u64 v[120:121], v[158:159], 0, v[126:127]
	v_max_f32_e32 v112, 0, v112
	v_max_f32_e32 v113, 0, v113
	global_store_dwordx4 v[120:121], v[122:125], off
	s_nop 1
	v_pk_mul_f32 v[122:123], v[112:113], v[112:113]
	v_max_f32_e32 v113, v114, v114
	v_max_f32_e32 v112, v118, v118
	v_max_f32_e32 v114, 0, v113
	v_max_f32_e32 v113, v119, v119
	v_max_f32_e32 v116, 0, v116
	v_max_f32_e32 v117, 0, v117
	v_max_f32_e32 v112, 0, v112
	v_max_f32_e32 v113, 0, v113
	v_max_f32_e32 v115, 0, v115
	v_pk_mul_f32 v[116:117], v[116:117], v[116:117]
	v_pk_mul_f32 v[118:119], v[112:113], v[112:113]
	v_pk_mul_f32 v[124:125], v[114:115], v[114:115]
	v_cvt_pk_bf16_f32 v112, v116, v117
	v_cvt_pk_bf16_f32 v113, v118, v119
	v_cvt_pk_bf16_f32 v114, v122, v123
	v_cvt_pk_bf16_f32 v115, v124, v125
	v_max_f32_e32 v104, 0, v104
	v_max_f32_e32 v105, 0, v105
	global_store_dwordx4 v[120:121], v[112:115], off offset:256
	s_nop 1
	v_or_b32_e32 v112, 16, v154
	v_pk_mul_f32 v[114:115], v[104:105], v[104:105]
	v_max_f32_e32 v105, v106, v106
	v_ashrrev_i32_e32 v113, 31, v112
	v_max_f32_e32 v104, v110, v110
	v_max_f32_e32 v106, 0, v105
	v_max_f32_e32 v105, v111, v111
	v_lshlrev_b64 v[112:113], 13, v[112:113]
	v_max_f32_e32 v108, 0, v108
	v_max_f32_e32 v109, 0, v109
	v_max_f32_e32 v104, 0, v104
	v_max_f32_e32 v105, 0, v105
	v_max_f32_e32 v107, 0, v107
	v_lshl_add_u64 v[112:113], s[46:47], 0, v[112:113]
	v_pk_mul_f32 v[108:109], v[108:109], v[108:109]
	v_pk_mul_f32 v[110:111], v[104:105], v[104:105]
	v_pk_mul_f32 v[116:117], v[106:107], v[106:107]
	v_cvt_pk_bf16_f32 v104, v108, v109
	v_cvt_pk_bf16_f32 v105, v110, v111
	v_cvt_pk_bf16_f32 v106, v114, v115
	v_cvt_pk_bf16_f32 v107, v116, v117
	v_lshl_add_u64 v[108:109], v[112:113], 0, v[126:127]
	v_max_f32_e32 v96, 0, v96
	v_max_f32_e32 v97, 0, v97
	global_store_dwordx4 v[108:109], v[104:107], off
	s_nop 1
	v_pk_mul_f32 v[104:105], v[96:97], v[96:97]
	v_max_f32_e32 v97, v98, v98
	v_max_f32_e32 v96, v102, v102
	v_max_f32_e32 v98, 0, v97
	v_max_f32_e32 v97, v103, v103
	v_max_f32_e32 v100, 0, v100
	v_max_f32_e32 v101, 0, v101
	v_max_f32_e32 v96, 0, v96
	v_max_f32_e32 v97, 0, v97
	v_max_f32_e32 v99, 0, v99
	v_pk_mul_f32 v[100:101], v[100:101], v[100:101]
	v_pk_mul_f32 v[102:103], v[96:97], v[96:97]
	v_pk_mul_f32 v[106:107], v[98:99], v[98:99]
	v_cvt_pk_bf16_f32 v96, v100, v101
	v_cvt_pk_bf16_f32 v97, v102, v103
	v_cvt_pk_bf16_f32 v98, v104, v105
	v_cvt_pk_bf16_f32 v99, v106, v107
	v_max_f32_e32 v88, 0, v88
	v_max_f32_e32 v89, 0, v89
	global_store_dwordx4 v[108:109], v[96:99], off offset:256
	s_nop 1
	v_or_b32_e32 v96, 32, v154
	v_pk_mul_f32 v[98:99], v[88:89], v[88:89]
	v_max_f32_e32 v89, v90, v90
	v_ashrrev_i32_e32 v97, 31, v96
	v_max_f32_e32 v88, v94, v94
	v_max_f32_e32 v90, 0, v89
	v_max_f32_e32 v89, v95, v95
	v_lshlrev_b64 v[96:97], 13, v[96:97]
	v_max_f32_e32 v92, 0, v92
	v_max_f32_e32 v93, 0, v93
	v_max_f32_e32 v88, 0, v88
	v_max_f32_e32 v89, 0, v89
	v_max_f32_e32 v91, 0, v91
	v_lshl_add_u64 v[96:97], s[46:47], 0, v[96:97]
	v_pk_mul_f32 v[92:93], v[92:93], v[92:93]
	v_pk_mul_f32 v[94:95], v[88:89], v[88:89]
	v_pk_mul_f32 v[100:101], v[90:91], v[90:91]
	v_cvt_pk_bf16_f32 v88, v92, v93
	v_cvt_pk_bf16_f32 v89, v94, v95
	v_cvt_pk_bf16_f32 v90, v98, v99
	v_cvt_pk_bf16_f32 v91, v100, v101
	v_lshl_add_u64 v[92:93], v[96:97], 0, v[126:127]
	v_max_f32_e32 v80, 0, v80
	v_max_f32_e32 v81, 0, v81
	global_store_dwordx4 v[92:93], v[88:91], off
	s_nop 1
	v_pk_mul_f32 v[88:89], v[80:81], v[80:81]
	v_max_f32_e32 v81, v82, v82
	v_max_f32_e32 v80, v86, v86
	v_max_f32_e32 v82, 0, v81
	v_max_f32_e32 v81, v87, v87
	v_max_f32_e32 v84, 0, v84
	v_max_f32_e32 v85, 0, v85
	v_max_f32_e32 v80, 0, v80
	v_max_f32_e32 v81, 0, v81
	v_max_f32_e32 v83, 0, v83
	v_pk_mul_f32 v[84:85], v[84:85], v[84:85]
	v_pk_mul_f32 v[86:87], v[80:81], v[80:81]
	v_pk_mul_f32 v[90:91], v[82:83], v[82:83]
	v_cvt_pk_bf16_f32 v80, v84, v85
	v_cvt_pk_bf16_f32 v81, v86, v87
	v_cvt_pk_bf16_f32 v82, v88, v89
	v_cvt_pk_bf16_f32 v83, v90, v91
	v_max_f32_e32 v72, 0, v72
	v_max_f32_e32 v73, 0, v73
	global_store_dwordx4 v[92:93], v[80:83], off offset:256
	s_nop 1
	v_or_b32_e32 v80, 48, v154
	v_pk_mul_f32 v[82:83], v[72:73], v[72:73]
	v_max_f32_e32 v73, v74, v74
	v_ashrrev_i32_e32 v81, 31, v80
	v_max_f32_e32 v72, v78, v78
	v_max_f32_e32 v74, 0, v73
	v_max_f32_e32 v73, v79, v79
	v_lshlrev_b64 v[80:81], 13, v[80:81]
	v_max_f32_e32 v76, 0, v76
	v_max_f32_e32 v77, 0, v77
	v_max_f32_e32 v72, 0, v72
	v_max_f32_e32 v73, 0, v73
	v_max_f32_e32 v75, 0, v75
	v_lshl_add_u64 v[80:81], s[46:47], 0, v[80:81]
	v_pk_mul_f32 v[76:77], v[76:77], v[76:77]
	v_pk_mul_f32 v[78:79], v[72:73], v[72:73]
	v_pk_mul_f32 v[84:85], v[74:75], v[74:75]
	v_cvt_pk_bf16_f32 v72, v76, v77
	v_cvt_pk_bf16_f32 v73, v78, v79
	v_cvt_pk_bf16_f32 v74, v82, v83
	v_cvt_pk_bf16_f32 v75, v84, v85
	v_lshl_add_u64 v[76:77], v[80:81], 0, v[126:127]
	v_max_f32_e32 v64, 0, v64
	v_max_f32_e32 v65, 0, v65
	global_store_dwordx4 v[76:77], v[72:75], off
	s_nop 1
	v_pk_mul_f32 v[72:73], v[64:65], v[64:65]
	v_max_f32_e32 v65, v66, v66
	v_max_f32_e32 v64, v70, v70
	v_max_f32_e32 v66, 0, v65
	v_max_f32_e32 v65, v71, v71
	v_max_f32_e32 v68, 0, v68
	v_max_f32_e32 v69, 0, v69
	v_max_f32_e32 v64, 0, v64
	v_max_f32_e32 v65, 0, v65
	v_max_f32_e32 v67, 0, v67
	v_pk_mul_f32 v[68:69], v[68:69], v[68:69]
	v_pk_mul_f32 v[70:71], v[64:65], v[64:65]
	v_pk_mul_f32 v[74:75], v[66:67], v[66:67]
	v_cvt_pk_bf16_f32 v64, v68, v69
	v_cvt_pk_bf16_f32 v65, v70, v71
	v_cvt_pk_bf16_f32 v66, v72, v73
	v_cvt_pk_bf16_f32 v67, v74, v75
	v_max_f32_e32 v56, 0, v56
	v_max_f32_e32 v57, 0, v57
	global_store_dwordx4 v[76:77], v[64:67], off offset:256
	s_nop 1
	v_pk_mul_f32 v[64:65], v[56:57], v[56:57]
	v_max_f32_e32 v57, v58, v58
	v_max_f32_e32 v56, v62, v62
	v_max_f32_e32 v58, 0, v57
	v_max_f32_e32 v57, v63, v63
	v_max_f32_e32 v56, 0, v56
	v_max_f32_e32 v57, 0, v57
	v_max_f32_e32 v60, 0, v60
	v_max_f32_e32 v61, 0, v61
	v_max_f32_e32 v59, 0, v59
	v_pk_mul_f32 v[62:63], v[56:57], v[56:57]
	v_pk_mul_f32 v[60:61], v[60:61], v[60:61]
	v_pk_mul_f32 v[66:67], v[58:59], v[58:59]
	v_cvt_pk_bf16_f32 v57, v62, v63
	v_add_co_u32_e32 v62, vcc, s64, v120
	v_cvt_pk_bf16_f32 v56, v60, v61
	v_cvt_pk_bf16_f32 v58, v64, v65
	v_cvt_pk_bf16_f32 v59, v66, v67
	v_addc_co_u32_e32 v63, vcc, 0, v121, vcc
	v_max_f32_e32 v48, 0, v48
	v_max_f32_e32 v49, 0, v49
	global_store_dwordx4 v[62:63], v[56:59], off
	s_nop 1
	v_pk_mul_f32 v[56:57], v[48:49], v[48:49]
	v_max_f32_e32 v49, v50, v50
	v_max_f32_e32 v48, v54, v54
	v_max_f32_e32 v50, 0, v49
	v_max_f32_e32 v49, v55, v55
	v_max_f32_e32 v52, 0, v52
	v_max_f32_e32 v53, 0, v53
	v_max_f32_e32 v48, 0, v48
	v_max_f32_e32 v49, 0, v49
	v_max_f32_e32 v51, 0, v51
	v_pk_mul_f32 v[52:53], v[52:53], v[52:53]
	v_pk_mul_f32 v[54:55], v[48:49], v[48:49]
	v_pk_mul_f32 v[58:59], v[50:51], v[50:51]
	v_lshl_add_u64 v[60:61], v[120:121], 0, s[12:13]
	v_cvt_pk_bf16_f32 v48, v52, v53
	v_cvt_pk_bf16_f32 v49, v54, v55
	v_cvt_pk_bf16_f32 v50, v56, v57
	v_cvt_pk_bf16_f32 v51, v58, v59
	v_max_f32_e32 v40, 0, v40
	v_max_f32_e32 v41, 0, v41
	global_store_dwordx4 v[60:61], v[48:51], off offset:256
	s_nop 1
	v_pk_mul_f32 v[48:49], v[40:41], v[40:41]
	v_max_f32_e32 v41, v42, v42
	v_max_f32_e32 v40, v46, v46
	v_max_f32_e32 v42, 0, v41
	v_max_f32_e32 v41, v47, v47
	v_max_f32_e32 v40, 0, v40
	v_max_f32_e32 v41, 0, v41
	v_max_f32_e32 v44, 0, v44
	v_max_f32_e32 v45, 0, v45
	v_max_f32_e32 v43, 0, v43
	v_pk_mul_f32 v[46:47], v[40:41], v[40:41]
	v_pk_mul_f32 v[44:45], v[44:45], v[44:45]
	v_pk_mul_f32 v[50:51], v[42:43], v[42:43]
	v_cvt_pk_bf16_f32 v41, v46, v47
	v_add_co_u32_e32 v46, vcc, s65, v120
	v_cvt_pk_bf16_f32 v40, v44, v45
	v_cvt_pk_bf16_f32 v42, v48, v49
	v_cvt_pk_bf16_f32 v43, v50, v51
	v_addc_co_u32_e32 v47, vcc, 0, v121, vcc
	v_max_f32_e32 v32, 0, v32
	v_max_f32_e32 v33, 0, v33
	global_store_dwordx4 v[46:47], v[40:43], off
	s_nop 1
	v_pk_mul_f32 v[40:41], v[32:33], v[32:33]
	v_max_f32_e32 v33, v34, v34
	v_max_f32_e32 v32, v38, v38
	v_max_f32_e32 v34, 0, v33
	v_max_f32_e32 v33, v39, v39
	v_max_f32_e32 v36, 0, v36
	v_max_f32_e32 v37, 0, v37
	v_max_f32_e32 v32, 0, v32
	v_max_f32_e32 v33, 0, v33
	v_max_f32_e32 v35, 0, v35
	v_pk_mul_f32 v[36:37], v[36:37], v[36:37]
	v_pk_mul_f32 v[38:39], v[32:33], v[32:33]
	v_pk_mul_f32 v[42:43], v[34:35], v[34:35]
	v_lshl_add_u64 v[44:45], v[120:121], 0, s[14:15]
	v_cvt_pk_bf16_f32 v32, v36, v37
	v_cvt_pk_bf16_f32 v33, v38, v39
	v_cvt_pk_bf16_f32 v34, v40, v41
	v_cvt_pk_bf16_f32 v35, v42, v43
	v_max_f32_e32 v24, 0, v24
	v_max_f32_e32 v25, 0, v25
	global_store_dwordx4 v[44:45], v[32:35], off offset:256
	s_nop 1
	v_pk_mul_f32 v[32:33], v[24:25], v[24:25]
	v_max_f32_e32 v25, v26, v26
	v_max_f32_e32 v24, v30, v30
	v_max_f32_e32 v26, 0, v25
	v_max_f32_e32 v25, v31, v31
	v_max_f32_e32 v24, 0, v24
	v_max_f32_e32 v25, 0, v25
	v_max_f32_e32 v28, 0, v28
	v_max_f32_e32 v29, 0, v29
	v_max_f32_e32 v27, 0, v27
	v_pk_mul_f32 v[30:31], v[24:25], v[24:25]
	v_pk_mul_f32 v[28:29], v[28:29], v[28:29]
	v_pk_mul_f32 v[34:35], v[26:27], v[26:27]
	v_cvt_pk_bf16_f32 v25, v30, v31
	v_add_co_u32_e32 v30, vcc, s70, v120
	v_cvt_pk_bf16_f32 v24, v28, v29
	v_cvt_pk_bf16_f32 v26, v32, v33
	v_cvt_pk_bf16_f32 v27, v34, v35
	v_addc_co_u32_e32 v31, vcc, 0, v121, vcc
	v_max_f32_e32 v16, 0, v16
	v_max_f32_e32 v17, 0, v17
	global_store_dwordx4 v[30:31], v[24:27], off
	s_nop 1
	v_pk_mul_f32 v[24:25], v[16:17], v[16:17]
	v_max_f32_e32 v17, v18, v18
	v_max_f32_e32 v16, v22, v22
	v_max_f32_e32 v18, 0, v17
	v_max_f32_e32 v17, v23, v23
	v_max_f32_e32 v20, 0, v20
	v_max_f32_e32 v21, 0, v21
	v_max_f32_e32 v16, 0, v16
	v_max_f32_e32 v17, 0, v17
	v_max_f32_e32 v19, 0, v19
	v_pk_mul_f32 v[20:21], v[20:21], v[20:21]
	v_pk_mul_f32 v[22:23], v[16:17], v[16:17]
	v_pk_mul_f32 v[26:27], v[18:19], v[18:19]
	v_lshl_add_u64 v[28:29], v[120:121], 0, s[16:17]
	v_cvt_pk_bf16_f32 v16, v20, v21
	v_cvt_pk_bf16_f32 v17, v22, v23
	v_cvt_pk_bf16_f32 v18, v24, v25
	v_cvt_pk_bf16_f32 v19, v26, v27
	v_max_f32_e32 v8, 0, v8
	v_max_f32_e32 v9, 0, v9
	global_store_dwordx4 v[28:29], v[16:19], off offset:256
	s_nop 1
	v_pk_mul_f32 v[16:17], v[8:9], v[8:9]
	v_max_f32_e32 v9, v10, v10
	v_max_f32_e32 v8, v14, v14
	v_max_f32_e32 v10, 0, v9
	v_max_f32_e32 v9, v15, v15
	v_max_f32_e32 v8, 0, v8
	v_max_f32_e32 v9, 0, v9
	v_max_f32_e32 v12, 0, v12
	v_max_f32_e32 v13, 0, v13
	v_max_f32_e32 v11, 0, v11
	v_pk_mul_f32 v[14:15], v[8:9], v[8:9]
	v_pk_mul_f32 v[12:13], v[12:13], v[12:13]
	v_pk_mul_f32 v[18:19], v[10:11], v[10:11]
	v_cvt_pk_bf16_f32 v9, v14, v15
	v_add_co_u32_e32 v14, vcc, s71, v120
	v_cvt_pk_bf16_f32 v8, v12, v13
	v_cvt_pk_bf16_f32 v10, v16, v17
	v_cvt_pk_bf16_f32 v11, v18, v19
	v_addc_co_u32_e32 v15, vcc, 0, v121, vcc
	v_max_f32_e32 v0, 0, v0
	v_max_f32_e32 v1, 0, v1
	global_store_dwordx4 v[14:15], v[8:11], off
	s_nop 1
	v_pk_mul_f32 v[8:9], v[0:1], v[0:1]
	v_max_f32_e32 v1, v2, v2
	v_max_f32_e32 v0, v6, v6
	v_max_f32_e32 v2, 0, v1
	v_max_f32_e32 v1, v7, v7
	v_max_f32_e32 v4, 0, v4
	v_max_f32_e32 v5, 0, v5
	v_max_f32_e32 v0, 0, v0
	v_max_f32_e32 v1, 0, v1
	v_max_f32_e32 v3, 0, v3
	v_pk_mul_f32 v[4:5], v[4:5], v[4:5]
	v_pk_mul_f32 v[6:7], v[0:1], v[0:1]
	v_pk_mul_f32 v[10:11], v[2:3], v[2:3]
	v_lshl_add_u64 v[12:13], v[120:121], 0, s[18:19]
	v_cvt_pk_bf16_f32 v0, v4, v5
	v_cvt_pk_bf16_f32 v1, v6, v7
	v_cvt_pk_bf16_f32 v2, v8, v9
	v_cvt_pk_bf16_f32 v3, v10, v11
	s_and_b64 vcc, exec, s[4:5]
	s_mov_b32 s72, s20
	s_mov_b32 s34, s26
	s_mov_b64 s[38:39], s[30:31]
	s_mov_b64 s[36:37], s[28:29]
	global_store_dwordx4 v[12:13], v[0:3], off offset:256
	s_cbranch_vccz .LBB0_1303
	s_waitcnt vmcnt(16)
	s_cmpk_gt_u32 s42, 0xff
	s_cbranch_scc1 .LBB0_1314
	s_barrier
